# v10 + row-pass and pool loops keep next-row prefetch in flight (waits moved into the conditional reload blocks, counted latch waits)
# speedup vs baseline: 1.0087x; 1.0087x over previous
; DI unsigned pk2c(float lo, float hi) { unsigned r; asm("v_cvt_pk_bf16_f32 %0, %1, %2" : "=v"(r) : "v"(lo), "v"(hi)); return r; }
; DI float bflo(unsigned w) { return __uint_as_float(w << 16); }
; DI float bfhi(unsigned w) { return __uint_as_float(w & 0xffff0000u); }
; DI void pool_rows(const Cx& a, int l, int tid, int gw, int NGW) {
;     const int lane = tid & 63;
;     bf16_t* Z = (bf16_t*)(a.ws + WS_Z);
;     const int chunk = (ROWS + NGW - 1) / NGW; const int r0 = gw * chunk; const int r1 = (r0 + chunk < ROWS) ? r0 + chunk : ROWS;
;     if (r0 >= r1) return;
;     const int g = lane >> 4, hw = 1 << g;
;     const bf16_t* ucol = Z + ZC_U + lane * 8;
;     float sum[8];
; #pragma unroll
;     for (int e = 0; e < 8; ++e) sum[e] = 0.f;
;     ...
;     u32x4 wa, wr, ws_, na, nr, ns;
;     PL_LOAD(r0, wa, wr, ws_);
;     bool need_init = true;
;     ...
;             const float ic = 1.f / (float)(hi_ - lo);
;             u32x4 o; o.x = pk2c(sum[0] * ic - bflo(ws_.x), sum[1] * ic - bfhi(ws_.x)); o.y = pk2c(sum[2] * ic - bflo(ws_.y), sum[3] * ic - bfhi(ws_.y));
;             o.z = pk2c(sum[4] * ic - bflo(ws_.z), sum[5] * ic - bfhi(ws_.z)); o.w = pk2c(sum[6] * ic - bflo(ws_.w), sum[7] * ic - bfhi(ws_.w));
;             *(u32x4*)(Z + (size_t)row * ZLD + ZC_PL + lane * 8) = o;
;         }
;         wa = na; wr = nr; ws_ = ns;
.LBB0_606:
	s_lshl_b32 s1, s1, 3
	s_abs_i32 s4, s1
	v_cvt_f32_u32_e32 v1, s4
	v_mov_b32_e32 v0, v196
	v_rcp_iflag_f32_e32 v1, v1
	v_ashrrev_i32_e32 v2, 6, v0
	v_lshl_add_u32 v2, s0, 3, v2
	s_add_i32 s0, s1, 0x10fff
	v_mul_f32_e32 v1, 0x4f7ffffe, v1
	v_cvt_u32_f32_e32 v1, v1
	s_xor_b32 s5, s0, s1
	s_sub_i32 s1, 0xfffef001, s1
	s_max_i32 s0, s0, s1
	s_sub_i32 s1, 0, s4
	v_readfirstlane_b32 s6, v1
	s_mul_i32 s1, s1, s6
	s_mul_hi_u32 s1, s6, s1
	s_add_i32 s6, s6, s1
	s_mul_hi_u32 s1, s0, s6
	s_mul_i32 s6, s1, s4
	s_sub_i32 s0, s0, s6
	s_ashr_i32 s5, s5, 31
	s_add_i32 s6, s1, 1
	s_sub_i32 s7, s0, s4
	s_cmp_ge_u32 s0, s4
	s_cselect_b32 s1, s6, s1
	s_cselect_b32 s0, s7, s0
	s_add_i32 s6, s1, 1
	s_cmp_ge_u32 s0, s4
	s_cselect_b32 s0, s6, s1
	s_xor_b32 s0, s0, s5
	s_sub_i32 s0, s0, s5
	v_mul_lo_u32 v36, v2, s0
	v_add_u32_e32 v1, s0, v36
	v_min_i32_e32 v45, 0x11000, v1
	v_cmp_lt_i32_e32 vcc, v36, v45
	s_and_saveexec_b64 s[0:1], vcc
	s_cbranch_execz .LBB0_617
	v_mul_hi_i32 v2, v36, s59
	v_lshrrev_b32_e32 v3, 31, v2
	v_ashrrev_i32_e32 v2, 11, v2
	v_add_u32_e32 v2, v2, v3
	v_mul_i32_i24_e32 v2, 0x1100, v2
	v_and_b32_e32 v1, 63, v0
	v_bfe_u32 v0, v0, 4, 2
	v_sub_u32_e32 v2, v36, v2
	v_lshlrev_b32_e64 v44, v0, 1
	v_add_u32_e32 v3, 0xfffff000, v2
	v_cmp_gt_i32_e32 vcc, s33, v2
	v_not_b32_e32 v56, v44
	v_lshlrev_b32_e32 v96, 4, v1
	v_cndmask_b32_e32 v6, v3, v2, vcc
	v_add_u32_e32 v2, v6, v56
	v_lshl_add_u64 v[0:1], s[2:3], 0, v[96:97]
	s_mov_b64 s[4:5], 0xc200c00
	v_max_i32_e32 v2, 0, v2
	v_sub_u32_e32 v7, v36, v6
	v_lshl_add_u64 v[46:47], v[0:1], 0, s[4:5]
	v_add_u32_e32 v2, v2, v7
	v_mad_i64_i32 v[0:1], s[4:5], v36, s35, v[46:47]
	v_mad_i64_i32 v[4:5], s[4:5], v2, s35, v[46:47]
	global_load_dwordx4 v[0:3], v[0:1], off
	s_nop 0
	global_load_dwordx4 v[16:19], v[4:5], off
	v_add_u32_e32 v4, v6, v44
	v_cndmask_b32_e32 v5, v233, v197, vcc
	v_min_i32_e32 v4, v4, v5
	v_add3_u32 v4, v7, v4, -1
	v_mad_i64_i32 v[4:5], s[4:5], v4, s35, v[46:47]
	global_load_dwordx4 v[20:23], v[4:5], off
	v_mad_i64_i32 v[4:5], s[4:5], v36, s35, v[96:97]
	v_lshl_add_u64 v[4:5], s[2:3], 0, v[4:5]
	s_mov_b64 s[2:3], 0xc200400
	v_mov_b32_e32 v50, 0
	v_lshl_add_u64 v[48:49], v[4:5], 0, s[2:3]
	s_mov_b64 s[14:15], -1
	s_mov_b64 s[4:5], 0
	v_mov_b32_e32 v51, v50
	v_mov_b32_e32 v24, v50
	v_mov_b32_e32 v25, v50
	v_mov_b32_e32 v26, v50
	v_mov_b32_e32 v27, v50
	v_mov_b32_e32 v28, v50
	v_mov_b32_e32 v29, v50
	s_waitcnt vmcnt(0)
	s_branch .LBB0_610
.LBB0_608:
	s_or_b64 exec, exec, s[14:15]
	v_sub_u32_e32 v16, v59, v58
	v_cvt_f32_i32_e32 v16, v16
	v_div_scale_f32 v17, s[14:15], v16, v16, 1.0
	v_rcp_f32_e32 v18, v17
	s_nop 0
	v_fma_f32 v19, -v17, v18, 1.0
	v_fmac_f32_e32 v18, v19, v18
	v_div_scale_f32 v19, vcc, 1.0, v16, 1.0
	v_mul_f32_e32 v20, v19, v18
	v_fma_f32 v21, -v17, v20, v19
	v_fmac_f32_e32 v20, v21, v18
	v_fma_f32 v17, -v17, v20, v19
	v_div_fmas_f32 v17, v17, v18, v20
	v_div_fixup_f32 v16, v17, v16, 1.0
	v_lshlrev_b32_e32 v17, 16, v0
	v_and_b32_e32 v0, 0xffff0000, v0
	v_fma_f32 v17, v16, v50, -v17
	v_fma_f32 v0, v16, v51, -v0
	v_cvt_pk_bf16_f32 v0, v17, v0
	v_lshlrev_b32_e32 v17, 16, v1
	v_and_b32_e32 v1, 0xffff0000, v1
	v_fma_f32 v17, v16, v24, -v17
	v_fma_f32 v1, v16, v25, -v1
	v_cvt_pk_bf16_f32 v1, v17, v1
	v_lshlrev_b32_e32 v17, 16, v2
	v_and_b32_e32 v2, 0xffff0000, v2
	v_fma_f32 v17, v16, v26, -v17
	v_fma_f32 v2, v16, v27, -v2
	v_cvt_pk_bf16_f32 v2, v17, v2
	v_lshlrev_b32_e32 v17, 16, v3
	v_and_b32_e32 v3, 0xffff0000, v3
	v_fma_f32 v3, v16, v29, -v3
	v_fma_f32 v17, v16, v28, -v17
	v_cvt_pk_bf16_f32 v3, v17, v3
	global_store_dwordx4 v[48:49], v[0:3], off
	s_waitcnt vmcnt(1)
.LBB0_609:
	s_or_b64 exec, exec, s[8:9]
	s_and_b64 s[2:3], exec, s[2:3]
	s_or_b64 s[4:5], s[2:3], s[4:5]
	s_mov_b64 s[2:3], 0x2e00
	v_mov_b64_e32 v[22:23], v[6:7]
	v_mov_b64_e32 v[18:19], v[10:11]
	v_mov_b64_e32 v[0:1], v[12:13]
	v_lshl_add_u64 v[48:49], v[48:49], 0, s[2:3]
	s_mov_b64 s[14:15], s[6:7]
	v_mov_b64_e32 v[20:21], v[4:5]
	v_mov_b64_e32 v[16:17], v[8:9]
	v_mov_b64_e32 v[2:3], v[14:15]
	v_mov_b32_e32 v36, v57
	s_andn2_b64 exec, exec, s[4:5]
	s_cbranch_execz .LBB0_617

; #define PL_ACC(W, F) do { sum[0] += (F) * bflo(W.x); sum[1] += (F) * bfhi(W.x); sum[2] += (F) * bflo(W.y); sum[3] += (F) * bfhi(W.y); sum[4] += (F) * bflo(W.z); sum[5] += (F) * bfhi(W.z); sum[6] += (F) * bflo(W.w); sum[7] += (F) * bfhi(W.w); } while (0)
; DI void pool_rows(const Cx& a, int l, int tid, int gw, int NGW) {
;     ...
;     for (int row = r0; row < r1; ++row) {
;         if (row + 1 < r1) PL_LOAD(row + 1, na, nr, ns);
;         const int b = row / NB, n = row - b * NB; const bool lat = n < SEQ; const int t = lat ? n : n - SEQ, nseq = lat ? SEQ : CTXL; const int rbase = row - t;
;         if (l == DEPTH - 1 && !lat) { need_init = true; }
;         else {
;             const int lo = t - hw < 0 ? 0 : t - hw, hi_ = t + hw > nseq ? nseq : t + hw;
;             if (need_init || t == 0) {
;                 need_init = false;
; #pragma unroll
;                 for (int e = 0; e < 8; ++e) sum[e] = 0.f;
;                 u32x4 w[16];
; #pragma unroll
;                 for (int jj = 0; jj < 16; ++jj) { int j = lo + jj; j = j < hi_ ? j : hi_ - 1; w[jj] = *(const u32x4*)(ucol + (size_t)(rbase + j) * ZLD); }
; #pragma unroll
;                 for (int jj = 0; jj < 16; ++jj) { const float f = (lo + jj < hi_) ? 1.f : 0.f; PL_ACC(w[jj], f); }
;             } else {
;                 const float fa = (t + hw - 1 < nseq) ? 1.f : 0.f, fr = (t - 1 - hw >= 0) ? -1.f : 0.f;
;                 PL_ACC(wa, fa); PL_ACC(wr, fr);
;             }
.LBB0_612:
	s_or_b64 exec, exec, s[6:7]
	v_mul_hi_i32 v30, v36, s59
	v_lshrrev_b32_e32 v31, 31, v30
	v_ashrrev_i32_e32 v30, 11, v30
	v_add_u32_e32 v30, v30, v31
	v_mul_i32_i24_e32 v30, 0x1100, v30
	v_sub_u32_e32 v30, v36, v30
	v_cmp_lt_i32_e32 vcc, s50, v30
	s_and_b64 s[6:7], s[12:13], vcc
	s_xor_b64 s[16:17], s[6:7], -1
	s_and_saveexec_b64 s[8:9], s[16:17]
	s_cbranch_execz .Lpool_skip
	v_add_u32_e32 v31, 0xfffff000, v30
	v_cndmask_b32_e32 v37, v30, v31, vcc
	v_cndmask_b32_e32 v30, v197, v233, vcc
	v_cmp_ne_u32_e32 vcc, 0, v37
	s_xor_b64 s[14:15], s[14:15], -1
	v_add_u32_e32 v31, v37, v44
	s_and_b64 s[14:15], s[14:15], vcc
	s_and_saveexec_b64 s[16:17], s[14:15]
	s_xor_b64 s[14:15], exec, s[16:17]
	s_cbranch_execz .LBB0_615
	v_cmp_lt_i32_e32 vcc, v30, v31
	v_and_b32_e32 v39, 0xffff0000, v23
	v_and_b32_e32 v38, 0xffff0000, v19
	v_cndmask_b32_e64 v33, 1.0, 0, vcc
	v_cmp_lt_i32_e32 vcc, v44, v37
	v_lshlrev_b32_e32 v34, 16, v23
	v_lshlrev_b32_e32 v35, 16, v19
	v_cndmask_b32_e64 v32, 0, -1.0, vcc
	v_pk_mul_f32 v[38:39], v[32:33], v[38:39]
	v_mul_f32_e32 v34, v33, v34
	v_lshlrev_b32_e32 v40, 16, v20
	v_and_b32_e32 v41, 0xffff0000, v20
	v_lshlrev_b32_e32 v42, 16, v16
	v_and_b32_e32 v43, 0xffff0000, v16
	v_mov_b32_e32 v16, v33
	v_lshlrev_b32_e32 v20, 16, v21
	v_and_b32_e32 v21, 0xffff0000, v21
	v_lshlrev_b32_e32 v54, 16, v22
	v_and_b32_e32 v55, 0xffff0000, v22
	v_lshlrev_b32_e32 v22, 16, v18
	v_and_b32_e32 v23, 0xffff0000, v18
	v_mul_f32_e32 v18, v32, v35
	v_mov_b32_e32 v35, v39
	v_lshlrev_b32_e32 v52, 16, v17
	v_and_b32_e32 v53, 0xffff0000, v17
	v_pk_fma_f32 v[20:21], v[16:17], v[20:21], v[24:25] op_sel_hi:[0,1,1]
	v_pk_add_f32 v[24:25], v[28:29], v[34:35]
	v_pk_fma_f32 v[34:35], v[16:17], v[40:41], v[50:51] op_sel_hi:[0,1,1]
	v_pk_fma_f32 v[16:17], v[16:17], v[54:55], v[26:27] op_sel_hi:[0,1,1]
	v_mov_b32_e32 v19, v38
	v_pk_add_f32 v[28:29], v[18:19], v[24:25]
	v_pk_fma_f32 v[24:25], v[32:33], v[52:53], v[20:21] op_sel_hi:[0,1,1]
	v_pk_fma_f32 v[26:27], v[32:33], v[22:23], v[16:17] op_sel_hi:[0,1,1]
	v_pk_fma_f32 v[50:51], v[32:33], v[42:43], v[34:35] op_sel_hi:[0,1,1]
.LBB0_615:
	s_or_saveexec_b64 s[14:15], s[14:15]
	v_sub_u32_e32 v16, v37, v44
	v_max_i32_e32 v58, 0, v16
	v_min_i32_e32 v59, v31, v30
	s_xor_b64 exec, exec, s[14:15]
	s_cbranch_execz .LBB0_608
	v_add_u32_e32 v40, -1, v59
	v_min_i32_e32 v16, v58, v40
	v_add_u32_e32 v51, 1, v58
	v_sub_u32_e32 v16, v16, v37
	v_min_i32_e32 v18, v51, v40
	v_add_u32_e32 v16, v36, v16
	v_sub_u32_e32 v18, v18, v37
	v_mad_i64_i32 v[16:17], s[16:17], v16, s35, v[46:47]
	v_add_u32_e32 v18, v36, v18
	v_add_u32_e32 v93, 2, v58
	v_mad_i64_i32 v[18:19], s[16:17], v18, s35, v[46:47]
	global_load_dwordx4 v[52:55], v[16:17], off
	global_load_dwordx4 v[60:63], v[18:19], off
	v_min_i32_e32 v16, v93, v40
	v_add_u32_e32 v95, 3, v58
	v_sub_u32_e32 v16, v16, v37
	v_min_i32_e32 v18, v95, v40
	v_add_u32_e32 v16, v36, v16
	v_sub_u32_e32 v18, v18, v37
	v_mad_i64_i32 v[16:17], s[16:17], v16, s35, v[46:47]
	v_add_u32_e32 v18, v36, v18
	v_add_u32_e32 v100, 4, v58
	v_mad_i64_i32 v[18:19], s[16:17], v18, s35, v[46:47]
	global_load_dwordx4 v[64:67], v[16:17], off
	global_load_dwordx4 v[68:71], v[18:19], off
	v_add_u32_e32 v98, 5, v58
	v_min_i32_e32 v16, v100, v40
	v_sub_u32_e32 v16, v16, v37
	v_min_i32_e32 v18, v98, v40
	v_add_u32_e32 v16, v36, v16
	v_sub_u32_e32 v18, v18, v37
	v_mad_i64_i32 v[16:17], s[16:17], v16, s35, v[46:47]
	v_add_u32_e32 v18, v36, v18
	v_mad_i64_i32 v[18:19], s[16:17], v18, s35, v[46:47]
	global_load_dwordx4 v[72:75], v[16:17], off
	global_load_dwordx4 v[76:79], v[18:19], off
	v_add_u32_e32 v104, 7, v58
	v_add_u32_e32 v105, 6, v58
	v_min_i32_e32 v16, v105, v40
	v_min_i32_e32 v18, v104, v40
	v_sub_u32_e32 v16, v16, v37
	v_sub_u32_e32 v18, v18, v37
	v_add_u32_e32 v16, v36, v16
	v_add_u32_e32 v18, v36, v18
	v_mad_i64_i32 v[16:17], s[16:17], v16, s35, v[46:47]
	v_mad_i64_i32 v[18:19], s[16:17], v18, s35, v[46:47]
	v_add_u32_e32 v106, 9, v58
	v_add_u32_e32 v107, 8, v58
	v_add_u32_e32 v108, 11, v58
	v_add_u32_e32 v110, 10, v58
	global_load_dwordx4 v[80:83], v[16:17], off
	global_load_dwordx4 v[84:87], v[18:19], off
	v_min_i32_e32 v16, v107, v40
	v_min_i32_e32 v18, v106, v40
	s_waitcnt vmcnt(8)
	v_min_i32_e32 v20, v110, v40
	v_min_i32_e32 v22, v108, v40
	v_sub_u32_e32 v16, v16, v37
	v_sub_u32_e32 v18, v18, v37
	v_sub_u32_e32 v20, v20, v37
	v_sub_u32_e32 v22, v22, v37
	v_add_u32_e32 v16, v36, v16
	v_add_u32_e32 v18, v36, v18
	v_add_u32_e32 v20, v36, v20
	v_add_u32_e32 v22, v36, v22
	v_mad_i64_i32 v[16:17], s[16:17], v16, s35, v[46:47]
	v_mad_i64_i32 v[18:19], s[16:17], v18, s35, v[46:47]
	v_mad_i64_i32 v[20:21], s[16:17], v20, s35, v[46:47]
	v_mad_i64_i32 v[22:23], s[16:17], v22, s35, v[46:47]
	global_load_dwordx4 v[88:91], v[16:17], off
	s_nop 0
	global_load_dwordx4 v[16:19], v[18:19], off
	s_nop 0
	global_load_dwordx4 v[24:27], v[20:21], off
	s_nop 0
	global_load_dwordx4 v[20:23], v[22:23], off
	v_add_u32_e32 v111, 13, v58
	v_add_u32_e32 v115, 12, v58
	v_min_i32_e32 v28, v115, v40
	v_min_i32_e32 v30, v111, v40
	v_sub_u32_e32 v28, v28, v37
	v_sub_u32_e32 v30, v30, v37
	v_add_u32_e32 v119, 15, v58
	v_add_u32_e32 v123, 14, v58
	v_add_u32_e32 v28, v36, v28
	v_add_u32_e32 v30, v36, v30
	v_min_i32_e32 v38, v123, v40
	v_min_i32_e32 v40, v119, v40
	v_mad_i64_i32 v[28:29], s[16:17], v28, s35, v[46:47]
	v_mad_i64_i32 v[30:31], s[16:17], v30, s35, v[46:47]
	v_sub_u32_e32 v38, v38, v37
	v_sub_u32_e32 v37, v40, v37
	global_load_dwordx4 v[32:35], v[28:29], off
	s_nop 0
	global_load_dwordx4 v[28:31], v[30:31], off
	v_add_u32_e32 v38, v36, v38
	v_add_u32_e32 v36, v36, v37
	v_mad_i64_i32 v[38:39], s[16:17], v38, s35, v[46:47]
	v_mad_i64_i32 v[36:37], s[16:17], v36, s35, v[46:47]
	global_load_dwordx4 v[40:43], v[38:39], off
	s_nop 0
	global_load_dwordx4 v[36:39], v[36:37], off
	v_cmp_gt_i32_e32 vcc, v59, v58
	s_waitcnt vmcnt(15)
; #define PL_ACC(W, F) do { sum[0] += (F) * bflo(W.x); sum[1] += (F) * bfhi(W.x); sum[2] += (F) * bflo(W.y); sum[3] += (F) * bfhi(W.y); sum[4] += (F) * bflo(W.z); sum[5] += (F) * bfhi(W.z); sum[6] += (F) * bflo(W.w); sum[7] += (F) * bfhi(W.w); } while (0)
; DI void pool_rows(const Cx& a, int l, int tid, int gw, int NGW) {
;     ...
;                 u32x4 w[16];
; #pragma unroll
;                 for (int jj = 0; jj < 16; ++jj) { int j = lo + jj; j = j < hi_ ? j : hi_ - 1; w[jj] = *(const u32x4*)(ucol + (size_t)(rbase + j) * ZLD); }
; #pragma unroll
;                 for (int jj = 0; jj < 16; ++jj) { const float f = (lo + jj < hi_) ? 1.f : 0.f; PL_ACC(w[jj], f); }
	v_and_b32_e32 v101, 0xffff0000, v52
	s_waitcnt vmcnt(14)
	v_lshlrev_b32_e32 v102, 16, v60
	v_cndmask_b32_e64 v50, 0, 1.0, vcc
	v_cmp_lt_i32_e32 vcc, v51, v59
	v_and_b32_e32 v103, 0xffff0000, v60
	v_lshlrev_b32_e32 v60, 16, v61
	v_cndmask_b32_e64 v92, 0, 1.0, vcc
	v_cmp_lt_i32_e32 vcc, v93, v59
	v_and_b32_e32 v61, 0xffff0000, v61
	s_waitcnt vmcnt(11)
	v_lshlrev_b32_e32 v51, 16, v75
	v_cndmask_b32_e64 v94, 0, 1.0, vcc
	v_cmp_lt_i32_e32 vcc, v95, v59
	s_waitcnt vmcnt(10)
	v_lshlrev_b32_e32 v93, 16, v79
	s_waitcnt vmcnt(5)
	v_and_b32_e32 v112, 0xffff0000, v27
	v_cndmask_b32_e64 v96, 0, 1.0, vcc
	v_cmp_lt_i32_e32 vcc, v98, v59
	s_waitcnt vmcnt(4)
	v_and_b32_e32 v113, 0xffff0000, v23
	s_waitcnt vmcnt(3)
	v_and_b32_e32 v120, 0xffff0000, v35
	v_cndmask_b32_e64 v99, 0, 1.0, vcc
	v_cmp_lt_i32_e32 vcc, v100, v59
	v_lshlrev_b32_e32 v100, 16, v52
	v_lshlrev_b32_e32 v52, 16, v53
	v_and_b32_e32 v53, 0xffff0000, v53
	v_pk_fma_f32 v[52:53], v[50:51], v[52:53], 0 op_sel_hi:[0,1,0]
	v_pk_fma_f32 v[52:53], v[92:93], v[60:61], v[52:53] op_sel_hi:[0,1,1]
	v_lshlrev_b32_e32 v60, 16, v65
	v_and_b32_e32 v61, 0xffff0000, v65
	v_pk_fma_f32 v[52:53], v[94:95], v[60:61], v[52:53] op_sel_hi:[0,1,1]
	v_lshlrev_b32_e32 v60, 16, v69
	v_and_b32_e32 v61, 0xffff0000, v69
	v_cndmask_b32_e64 v98, 0, 1.0, vcc
	v_pk_fma_f32 v[52:53], v[96:97], v[60:61], v[52:53] op_sel_hi:[0,1,1]
	v_lshlrev_b32_e32 v60, 16, v73
	v_and_b32_e32 v61, 0xffff0000, v73
	v_pk_fma_f32 v[100:101], v[50:51], v[100:101], 0 op_sel_hi:[0,1,0]
	v_pk_fma_f32 v[60:61], v[98:99], v[60:61], v[52:53] op_sel_hi:[0,1,1]
	v_lshlrev_b32_e32 v52, 16, v54
	v_and_b32_e32 v53, 0xffff0000, v54
	v_pk_fma_f32 v[100:101], v[92:93], v[102:103], v[100:101] op_sel_hi:[0,1,1]
	v_lshlrev_b32_e32 v102, 16, v64
	v_and_b32_e32 v103, 0xffff0000, v64
	v_pk_fma_f32 v[52:53], v[50:51], v[52:53], 0 op_sel_hi:[0,1,0]
	v_lshlrev_b32_e32 v64, 16, v62
	v_and_b32_e32 v65, 0xffff0000, v62
	v_pk_fma_f32 v[52:53], v[92:93], v[64:65], v[52:53] op_sel_hi:[0,1,1]
	v_lshlrev_b32_e32 v64, 16, v66
	v_and_b32_e32 v65, 0xffff0000, v66
	v_pk_fma_f32 v[100:101], v[94:95], v[102:103], v[100:101] op_sel_hi:[0,1,1]
	v_lshlrev_b32_e32 v102, 16, v68
	v_and_b32_e32 v103, 0xffff0000, v68
	v_pk_fma_f32 v[52:53], v[94:95], v[64:65], v[52:53] op_sel_hi:[0,1,1]
	v_lshlrev_b32_e32 v64, 16, v70
	v_and_b32_e32 v65, 0xffff0000, v70
	v_lshlrev_b32_e32 v68, 16, v55
	v_and_b32_e32 v69, 0xffff0000, v55
	v_pk_fma_f32 v[52:53], v[96:97], v[64:65], v[52:53] op_sel_hi:[0,1,1]
	v_lshlrev_b32_e32 v64, 16, v74
	v_and_b32_e32 v65, 0xffff0000, v74
	v_mul_f32_e32 v54, v98, v51
	v_pk_fma_f32 v[50:51], v[50:51], v[68:69], 0 op_sel_hi:[0,1,0]
	v_lshlrev_b32_e32 v62, 16, v63
	v_and_b32_e32 v63, 0xffff0000, v63
	v_pk_fma_f32 v[64:65], v[98:99], v[64:65], v[52:53] op_sel_hi:[0,1,1]
	v_and_b32_e32 v53, 0xffff0000, v79
	v_and_b32_e32 v52, 0xffff0000, v75
	v_pk_fma_f32 v[50:51], v[92:93], v[62:63], v[50:51] op_sel_hi:[0,1,1]
	v_lshlrev_b32_e32 v62, 16, v67
	v_and_b32_e32 v63, 0xffff0000, v67
	v_pk_mul_f32 v[52:53], v[98:99], v[52:53]
	v_pk_fma_f32 v[50:51], v[94:95], v[62:63], v[50:51] op_sel_hi:[0,1,1]
	v_lshlrev_b32_e32 v62, 16, v71
	v_and_b32_e32 v63, 0xffff0000, v71
	v_cmp_lt_i32_e32 vcc, v104, v59
	v_pk_fma_f32 v[50:51], v[96:97], v[62:63], v[50:51] op_sel_hi:[0,1,1]
	v_mov_b32_e32 v55, v52
	v_lshlrev_b32_e32 v68, 16, v78
	v_and_b32_e32 v69, 0xffff0000, v78
	v_lshlrev_b32_e32 v78, 16, v85
	v_and_b32_e32 v79, 0xffff0000, v85
	v_cndmask_b32_e64 v85, 0, 1.0, vcc
	v_cmp_lt_i32_e32 vcc, v105, v59
	v_pk_fma_f32 v[100:101], v[96:97], v[102:103], v[100:101] op_sel_hi:[0,1,1]
	v_lshlrev_b32_e32 v102, 16, v72
	v_and_b32_e32 v103, 0xffff0000, v72
	v_pk_add_f32 v[54:55], v[50:51], v[54:55]
	v_lshlrev_b32_e32 v50, 16, v76
	v_and_b32_e32 v51, 0xffff0000, v76
	v_lshlrev_b32_e32 v66, 16, v77
	v_and_b32_e32 v67, 0xffff0000, v77
	v_lshlrev_b32_e32 v76, 16, v84
	v_and_b32_e32 v77, 0xffff0000, v84
	v_cndmask_b32_e64 v84, 0, 1.0, vcc
	v_cmp_lt_i32_e32 vcc, v106, v59
	v_pk_fma_f32 v[100:101], v[98:99], v[102:103], v[100:101] op_sel_hi:[0,1,1]
	v_lshlrev_b32_e32 v63, 16, v83
	v_cndmask_b32_e64 v103, 0, 1.0, vcc
	v_cmp_lt_i32_e32 vcc, v107, v59
	v_lshlrev_b32_e32 v74, 16, v82
	v_and_b32_e32 v75, 0xffff0000, v82
	v_mul_f32_e32 v82, v84, v63
	v_lshlrev_b32_e32 v63, 16, v91
	v_cndmask_b32_e64 v102, 0, 1.0, vcc
	v_mov_b32_e32 v62, v99
	v_mul_f32_e32 v52, v99, v93
	v_lshlrev_b32_e32 v98, 16, v90
	v_and_b32_e32 v99, 0xffff0000, v90
	v_mul_f32_e32 v90, v102, v63
	v_lshlrev_b32_e32 v63, 16, v23
	v_lshlrev_b32_e32 v70, 16, v80
	v_and_b32_e32 v71, 0xffff0000, v80
	v_lshlrev_b32_e32 v72, 16, v81
	v_and_b32_e32 v73, 0xffff0000, v81
	v_pk_fma_f32 v[50:51], v[62:63], v[50:51], v[100:101] op_sel_hi:[0,1,1]
	v_pk_fma_f32 v[60:61], v[62:63], v[66:67], v[60:61] op_sel_hi:[0,1,1]
	v_pk_fma_f32 v[50:51], v[84:85], v[70:71], v[50:51] op_sel_hi:[0,1,1]
	v_mov_b32_e32 v70, v85
	v_pk_fma_f32 v[60:61], v[84:85], v[72:73], v[60:61] op_sel_hi:[0,1,1]
	v_lshlrev_b32_e32 v94, 16, v88
	v_and_b32_e32 v95, 0xffff0000, v88
	v_lshlrev_b32_e32 v88, 16, v89
	v_and_b32_e32 v89, 0xffff0000, v89
	v_cmp_lt_i32_e32 vcc, v108, v59
	v_pk_fma_f32 v[50:51], v[70:71], v[76:77], v[50:51] op_sel_hi:[0,1,1]
	v_pk_fma_f32 v[60:61], v[70:71], v[78:79], v[60:61] op_sel_hi:[0,1,1]
	v_cndmask_b32_e64 v109, 0, 1.0, vcc
	v_cmp_lt_i32_e32 vcc, v110, v59
	v_lshlrev_b32_e32 v76, 16, v16
	v_and_b32_e32 v77, 0xffff0000, v16
	v_pk_fma_f32 v[50:51], v[102:103], v[94:95], v[50:51] op_sel_hi:[0,1,1]
	v_mov_b32_e32 v16, v103
	v_lshlrev_b32_e32 v66, 16, v17
	v_and_b32_e32 v67, 0xffff0000, v17
	v_pk_fma_f32 v[60:61], v[102:103], v[88:89], v[60:61] op_sel_hi:[0,1,1]
	v_cndmask_b32_e64 v108, 0, 1.0, vcc
	v_cmp_lt_i32_e32 vcc, v111, v59
	v_pk_fma_f32 v[50:51], v[16:17], v[76:77], v[50:51] op_sel_hi:[0,1,1]
	v_lshlrev_b32_e32 v76, 16, v24
	v_and_b32_e32 v77, 0xffff0000, v24
	v_pk_fma_f32 v[60:61], v[16:17], v[66:67], v[60:61] op_sel_hi:[0,1,1]
	v_lshlrev_b32_e32 v24, 16, v25
	v_and_b32_e32 v25, 0xffff0000, v25
	v_cndmask_b32_e64 v117, 0, 1.0, vcc
	v_cmp_lt_i32_e32 vcc, v115, v59
	v_lshlrev_b32_e32 v94, 16, v20
	v_and_b32_e32 v95, 0xffff0000, v20
	v_mov_b32_e32 v20, v109
	v_lshlrev_b32_e32 v66, 16, v21
	v_and_b32_e32 v67, 0xffff0000, v21
	v_pk_fma_f32 v[24:25], v[108:109], v[24:25], v[60:61] op_sel_hi:[0,1,1]
	v_cndmask_b32_e64 v116, 0, 1.0, vcc
	v_cmp_lt_i32_e32 vcc, v119, v59
	v_pk_fma_f32 v[50:51], v[108:109], v[76:77], v[50:51] op_sel_hi:[0,1,1]
	v_pk_fma_f32 v[24:25], v[20:21], v[66:67], v[24:25] op_sel_hi:[0,1,1]
	v_lshlrev_b32_e32 v60, 16, v33
	v_and_b32_e32 v61, 0xffff0000, v33
	v_cndmask_b32_e64 v125, 0, 1.0, vcc
	v_cmp_lt_i32_e32 vcc, v123, v59
	v_pk_fma_f32 v[50:51], v[20:21], v[94:95], v[50:51] op_sel_hi:[0,1,1]
	v_lshlrev_b32_e32 v76, 16, v32
	v_and_b32_e32 v77, 0xffff0000, v32
	s_waitcnt vmcnt(2)
; #define PL_ACC(W, F) do { sum[0] += (F) * bflo(W.x); sum[1] += (F) * bfhi(W.x); sum[2] += (F) * bflo(W.y); sum[3] += (F) * bfhi(W.y); sum[4] += (F) * bflo(W.z); sum[5] += (F) * bfhi(W.z); sum[6] += (F) * bflo(W.w); sum[7] += (F) * bfhi(W.w); } while (0)
; DI void pool_rows(const Cx& a, int l, int tid, int gw, int NGW) {
;     ...
;                 for (int jj = 0; jj < 16; ++jj) { int j = lo + jj; j = j < hi_ ? j : hi_ - 1; w[jj] = *(const u32x4*)(ucol + (size_t)(rbase + j) * ZLD); }
; #pragma unroll
;                 for (int jj = 0; jj < 16; ++jj) { const float f = (lo + jj < hi_) ? 1.f : 0.f; PL_ACC(w[jj], f); }
;             } else {
;                 const float fa = (t + hw - 1 < nseq) ? 1.f : 0.f, fr = (t - 1 - hw >= 0) ? -1.f : 0.f;
;                 PL_ACC(wa, fa); PL_ACC(wr, fr);
	v_lshlrev_b32_e32 v94, 16, v28
	v_and_b32_e32 v95, 0xffff0000, v28
	v_mov_b32_e32 v28, v117
	v_lshlrev_b32_e32 v66, 16, v29
	v_and_b32_e32 v67, 0xffff0000, v29
	v_pk_fma_f32 v[24:25], v[116:117], v[60:61], v[24:25] op_sel_hi:[0,1,1]
	v_cndmask_b32_e64 v124, 0, 1.0, vcc
	v_pk_fma_f32 v[50:51], v[116:117], v[76:77], v[50:51] op_sel_hi:[0,1,1]
	s_waitcnt vmcnt(1)
	v_lshlrev_b32_e32 v76, 16, v40
	v_and_b32_e32 v77, 0xffff0000, v40
	v_pk_fma_f32 v[24:25], v[28:29], v[66:67], v[24:25] op_sel_hi:[0,1,1]
	v_lshlrev_b32_e32 v40, 16, v41
	v_and_b32_e32 v41, 0xffff0000, v41
	v_pk_fma_f32 v[50:51], v[28:29], v[94:95], v[50:51] op_sel_hi:[0,1,1]
	s_waitcnt vmcnt(0)
	v_lshlrev_b32_e32 v94, 16, v36
	v_and_b32_e32 v95, 0xffff0000, v36
	v_mov_b32_e32 v32, v125
	v_lshlrev_b32_e32 v36, 16, v37
	v_and_b32_e32 v37, 0xffff0000, v37
	v_pk_fma_f32 v[24:25], v[124:125], v[40:41], v[24:25] op_sel_hi:[0,1,1]
	v_lshlrev_b32_e32 v80, 16, v86
	v_and_b32_e32 v81, 0xffff0000, v86
	v_and_b32_e32 v86, 0xffff0000, v83
	v_lshlrev_b32_e32 v83, 16, v19
	v_and_b32_e32 v105, 0xffff0000, v19
	v_lshlrev_b32_e32 v19, 16, v27
	v_pk_fma_f32 v[24:25], v[32:33], v[36:37], v[24:25] op_sel_hi:[0,1,1]
	v_pk_fma_f32 v[36:37], v[62:63], v[68:69], v[64:65] op_sel_hi:[0,1,1]
	v_mul_f32_e32 v110, v108, v19
	v_lshlrev_b32_e32 v19, 16, v35
	v_pk_fma_f32 v[36:37], v[84:85], v[74:75], v[36:37] op_sel_hi:[0,1,1]
	v_mul_f32_e32 v118, v116, v19
	v_lshlrev_b32_e32 v19, 16, v43
	v_pk_fma_f32 v[36:37], v[70:71], v[80:81], v[36:37] op_sel_hi:[0,1,1]
	v_mul_f32_e32 v126, v124, v19
	v_lshlrev_b32_e32 v40, 16, v18
	v_and_b32_e32 v41, 0xffff0000, v18
	v_pk_fma_f32 v[18:19], v[102:103], v[98:99], v[36:37] op_sel_hi:[0,1,1]
	v_pk_fma_f32 v[16:17], v[16:17], v[40:41], v[18:19] op_sel_hi:[0,1,1]
	v_lshlrev_b32_e32 v18, 16, v26
	v_and_b32_e32 v19, 0xffff0000, v26
	v_lshlrev_b32_e32 v26, 16, v22
	v_and_b32_e32 v27, 0xffff0000, v22
	v_pk_fma_f32 v[16:17], v[108:109], v[18:19], v[16:17] op_sel_hi:[0,1,1]
	v_pk_fma_f32 v[16:17], v[20:21], v[26:27], v[16:17] op_sel_hi:[0,1,1]
	v_lshlrev_b32_e32 v18, 16, v34
	v_and_b32_e32 v19, 0xffff0000, v34
	v_lshlrev_b32_e32 v92, 16, v87
	v_and_b32_e32 v87, 0xffff0000, v87
	v_lshlrev_b32_e32 v20, 16, v30
	v_and_b32_e32 v21, 0xffff0000, v30
	v_pk_fma_f32 v[16:17], v[116:117], v[18:19], v[16:17] op_sel_hi:[0,1,1]
	v_pk_mul_f32 v[86:87], v[84:85], v[86:87]
	v_pk_fma_f32 v[16:17], v[28:29], v[20:21], v[16:17] op_sel_hi:[0,1,1]
	v_lshlrev_b32_e32 v18, 16, v42
	v_and_b32_e32 v19, 0xffff0000, v42
	v_and_b32_e32 v104, 0xffff0000, v91
	v_mul_f32_e32 v106, v103, v83
	v_pk_fma_f32 v[16:17], v[124:125], v[18:19], v[16:17] op_sel_hi:[0,1,1]
	v_pk_add_f32 v[18:19], v[54:55], v[52:53]
	v_mov_b32_e32 v83, v86
	v_mul_f32_e32 v92, v85, v92
	v_pk_mul_f32 v[104:105], v[102:103], v[104:105]
	v_pk_add_f32 v[18:19], v[18:19], v[82:83]
	v_mov_b32_e32 v93, v87
	v_pk_add_f32 v[18:19], v[18:19], v[92:93]
	v_mov_b32_e32 v91, v104
	v_pk_mul_f32 v[112:113], v[108:109], v[112:113]
	v_pk_add_f32 v[18:19], v[18:19], v[90:91]
	v_mov_b32_e32 v107, v105
	v_and_b32_e32 v121, 0xffff0000, v31
	v_pk_add_f32 v[18:19], v[18:19], v[106:107]
	v_mov_b32_e32 v111, v112
	v_mul_f32_e32 v114, v109, v63
	v_pk_mul_f32 v[120:121], v[116:117], v[120:121]
	v_pk_add_f32 v[18:19], v[18:19], v[110:111]
	v_mov_b32_e32 v115, v113
	v_lshlrev_b32_e32 v23, 16, v31
	v_and_b32_e32 v129, 0xffff0000, v39
	v_and_b32_e32 v128, 0xffff0000, v43
	v_pk_add_f32 v[18:19], v[18:19], v[114:115]
	v_mov_b32_e32 v119, v120
	v_mul_f32_e32 v122, v117, v23
	v_pk_mul_f32 v[128:129], v[124:125], v[128:129]
	v_pk_add_f32 v[18:19], v[18:19], v[118:119]
	v_mov_b32_e32 v123, v121
	v_lshlrev_b32_e32 v23, 16, v39
	v_lshlrev_b32_e32 v20, 16, v38
	v_and_b32_e32 v21, 0xffff0000, v38
	v_pk_add_f32 v[18:19], v[18:19], v[122:123]
	v_mov_b32_e32 v127, v128
	v_pk_fma_f32 v[50:51], v[124:125], v[76:77], v[50:51] op_sel_hi:[0,1,1]
	v_pk_fma_f32 v[26:27], v[32:33], v[20:21], v[16:17] op_sel_hi:[0,1,1]
	v_mul_f32_e32 v16, v125, v23
	v_pk_add_f32 v[18:19], v[18:19], v[126:127]
	v_mov_b32_e32 v17, v129
	v_pk_fma_f32 v[50:51], v[32:33], v[94:95], v[50:51] op_sel_hi:[0,1,1]
	v_pk_add_f32 v[28:29], v[18:19], v[16:17]
	s_branch .LBB0_608
.Lpool_skip:
	s_waitcnt vmcnt(0)
	s_branch .LBB0_609

; DI void rowpass(const Cx& a, int mode, int l, int tid, int gw, int NGW) {
;     const int lane = tid & 63;
;     const float* MOD = (const float*)(a.ws + WS_MOD); const float* SS = (const float*)(a.ws + WS_SS); bf16_t* H = (bf16_t*)(a.ws + WS_H);
;     bf16_t* XL = (bf16_t*)a.out; bf16_t* XCb = (bf16_t*)(a.ws + WS_XC); bf16_t* XA = (bf16_t*)(a.ws + WS_Z + 400 * MiB);
;     const float* normg = a.inp(6); const float* xin = a.inp(0); const float* cin = a.inp(2);
;     const int chunk = (ROWS + NGW - 1) / NGW; const int r0 = gw * chunk; const int r1 = (r0 + chunk < ROWS) ? r0 + chunk : ROWS;
;     if (r0 >= r1) return;
;     const bool lastl = (l == DEPTH - 1);
;     const bool last = (mode == 2 && lastl);
;     const bool skipc = (mode != 0 && lastl);
;     const int l2 = (mode == 2) ? l + 1 : l; const int k2 = (mode == 1) ? 2 : 0;
;     f32x4 gnv[4], g2v[4], gtv[4], shv[4], scv[4];
; #pragma unroll
;     for (int j = 0; j < 4; ++j) { const int c = 4 * lane + 256 * j;
;         gnv[j] = (mode == 0) ? (f32x4){0.f, 0.f, 0.f, 0.f} : *(const f32x4*)(normg + ((size_t)l * 4 + (mode == 1 ? 1 : 3)) * DM + c);
;         g2v[j] = last ? (f32x4){0.f, 0.f, 0.f, 0.f} : *(const f32x4*)(normg + ((size_t)l2 * 4 + k2) * DM + c);
;         gtv[j] = (f32x4){0.f, 0.f, 0.f, 0.f}; shv[j] = gtv[j]; scv[j] = gtv[j]; }
;     int cur_mv = -1;
;     f32x4 xfc[4], xfn[4]; u32x2 xbc[4], xbn[4]; u32x2 yc[4], yn[4]; float sc_ = 0.f, sn_ = 0.f;
;     ...
;     RP_LOAD(r0, xfc, xbc, yc, sc_);
.LBB0_983:
	s_lshl_b32 s1, s1, 3
	s_abs_i32 s5, s1
	v_cvt_f32_u32_e32 v0, s5
	v_mov_b32_e32 v33, v196
	s_add_i32 s9, s1, 0x10fff
	v_rcp_iflag_f32_e32 v0, v0
	v_ashrrev_i32_e32 v1, 6, v33
	s_xor_b32 s1, s9, s1
	s_sub_i32 s10, 0, s5
	v_mul_f32_e32 v0, 0x4f7ffffe, v0
	v_cvt_u32_f32_e32 v0, v0
	v_lshl_add_u32 v1, s0, 3, v1
	s_ashr_i32 s0, s1, 31
	s_abs_i32 s9, s9
	v_readfirstlane_b32 s1, v0
	s_mul_i32 s10, s10, s1
	s_mul_hi_u32 s10, s1, s10
	s_add_i32 s1, s1, s10
	s_mul_hi_u32 s1, s9, s1
	s_mul_i32 s10, s1, s5
	s_sub_i32 s9, s9, s10
	s_add_i32 s10, s1, 1
	s_sub_i32 s14, s9, s5
	s_cmp_ge_u32 s9, s5
	s_cselect_b32 s1, s10, s1
	s_cselect_b32 s9, s14, s9
	s_add_i32 s10, s1, 1
	s_cmp_ge_u32 s9, s5
	s_cselect_b32 s1, s10, s1
	s_xor_b32 s1, s1, s0
	s_sub_i32 s0, s1, s0
	v_mul_lo_u32 v130, v1, s0
	v_add_u32_e32 v0, s0, v130
	v_min_i32_e32 v81, 0x11000, v0
	v_readlane_b32 s0, v248, 25
	v_cmp_lt_i32_e32 vcc, v130, v81
	s_mul_hi_u32 s53, s0, 17
	s_mul_i32 s52, s0, 17
	v_readlane_b32 s1, v248, 26
	s_and_saveexec_b64 s[18:19], vcc
	s_cbranch_execz .LBB0_992
	s_add_u32 s20, s16, 0x100000
	s_addc_u32 s21, s17, 0
	s_add_u32 s9, s16, 0x2a00000
	s_addc_u32 s10, s17, 0
	s_add_u32 s0, s16, 0x25200000
	s_addc_u32 s1, s17, 0
	s_lshl_b32 s4, s4, 5
	s_ashr_i32 s5, s4, 31
	s_lshl_b64 s[4:5], s[4:5], 3
	s_add_u32 s4, s16, s4
	s_addc_u32 s5, s17, s5
	global_load_dwordx2 v[0:1], v197, s[4:5] offset:48
	v_lshlrev_b32_e32 v2, 2, v33
	v_ashrrev_i32_e32 v131, 31, v130
	v_and_b32_e32 v80, 0xfc, v2
	v_lshlrev_b64 v[82:83], 11, v[130:131]
	v_mov_b32_e32 v9, v97
	v_lshlrev_b64 v[40:41], 6, v[130:131]
	v_lshlrev_b32_e32 v8, 1, v80
	v_lshl_add_u64 v[12:13], s[16:17], 0, v[82:83]
	v_mul_hi_i32 v4, v130, s59
	v_mov_b32_e32 v39, v97
	v_and_b32_e32 v38, 60, v2
	v_lshl_add_u64 v[14:15], s[16:17], 0, v[40:41]
	v_lshl_add_u64 v[12:13], v[12:13], 0, v[8:9]
	s_mov_b64 s[4:5], 0x3a00000
	v_lshrrev_b32_e32 v6, 31, v4
	v_ashrrev_i32_e32 v4, 11, v4
	v_lshl_add_u64 v[42:43], v[14:15], 0, v[38:39]
	v_lshl_add_u64 v[14:15], v[12:13], 0, s[4:5]
	s_mov_b32 s4, 0x3a00000
	v_add_u32_e32 v10, v4, v6
	v_add_co_u32_e32 v12, vcc, s4, v12
	v_mad_i32_i24 v20, v10, s51, v130
	s_nop 0
	v_addc_co_u32_e32 v13, vcc, 0, v13, vcc
	v_mov_b32_e32 v16, s7
	v_mov_b32_e32 v18, s6
	v_mov_b32_e32 v19, s9
	v_add_u32_e32 v21, 0xfffff000, v20
	v_mov_b32_e32 v17, s10
	v_cmp_gt_i32_e32 vcc, s33, v20
	v_ashrrev_i32_e32 v11, 31, v10
	v_ashrrev_i32_e32 v22, 31, v20
	v_cndmask_b32_e32 v17, v17, v16, vcc
	v_cndmask_b32_e32 v16, v19, v18, vcc
	v_cndmask_b32_e32 v18, v21, v20, vcc
	v_cndmask_b32_e64 v20, 19, 23, vcc
	v_cndmask_b32_e32 v19, 0, v22, vcc
	v_lshlrev_b64 v[10:11], v20, v[10:11]
	v_readlane_b32 s4, v248, 25
	global_load_dwordx2 v[128:129], v[12:13], off
	global_load_dwordx2 v[124:125], v[14:15], off offset:512
	global_load_dwordx2 v[120:121], v[14:15], off offset:1024
	global_load_dwordx2 v[116:117], v[14:15], off offset:1536
	v_lshlrev_b64 v[12:13], 11, v[18:19]
	v_lshl_add_u64 v[10:11], v[16:17], 0, v[10:11]
	v_readlane_b32 s5, v248, 26
	v_lshl_add_u64 v[10:11], v[10:11], 0, v[12:13]
	s_lshl_b64 s[4:5], s[4:5], 14
	v_lshlrev_b32_e32 v96, 2, v80
	v_lshl_add_u64 v[8:9], v[10:11], 0, v[8:9]
	global_load_dwordx2 v[126:127], v[8:9], off
	global_load_dwordx2 v[122:123], v[8:9], off offset:512
	global_load_dwordx2 v[118:119], v[8:9], off offset:1024
	global_load_dwordx2 v[114:115], v[8:9], off offset:1536
	v_or_b32_e32 v36, 0x100, v80
	v_or_b32_e32 v34, 0x200, v80
	v_or_b32_e32 v32, 0x300, v80
	v_mov_b32_e32 v3, v97
	v_mov_b32_e32 v5, v97
	v_mov_b32_e32 v7, v97
	v_lshlrev_b32_e32 v2, 2, v36
	v_lshlrev_b32_e32 v4, 2, v34
	v_lshlrev_b32_e32 v6, 2, v32
	v_and_b32_e32 v33, 63, v33
	v_or_b32_e32 v40, v40, v38
	v_lshl_or_b32 v82, v33, 3, v82
	v_mov_b32_e32 v98, v97
	v_mov_b32_e32 v99, v97
	v_lshlrev_b32_e32 v88, 2, v36
	v_lshlrev_b32_e32 v90, 2, v34
	v_lshlrev_b32_e32 v92, 2, v32
	v_mov_b32_e32 v134, 0
	v_mov_b32_e32 v89, -1
	s_mov_b64 s[22:23], 0
	s_waitcnt vmcnt(8)
	v_lshl_add_u64 v[0:1], v[0:1], 0, s[4:5]
	v_lshl_add_u64 v[8:9], v[0:1], 0, s[88:89]
	v_lshl_add_u64 v[0:1], v[0:1], 0, v[96:97]
	s_mov_b64 s[4:5], 0x2000
	v_lshl_add_u64 v[28:29], v[0:1], 0, s[4:5]
	s_movk_i32 s4, 0x2000
	v_add_co_u32_e32 v0, vcc, s4, v0
	v_lshl_add_u64 v[10:11], v[8:9], 0, v[96:97]
	s_nop 0
	v_addc_co_u32_e32 v1, vcc, 0, v1, vcc
	v_lshl_add_u64 v[12:13], v[8:9], 0, v[2:3]
	v_lshl_add_u64 v[16:17], v[8:9], 0, v[4:5]
	v_lshl_add_u64 v[20:21], v[8:9], 0, v[6:7]
	flat_load_dwordx4 v[0:3], v[0:1]
	s_nop 0
	flat_load_dwordx4 v[4:7], v[12:13]
	s_nop 0
	flat_load_dwordx4 v[8:11], v[10:11]
	s_nop 0
	flat_load_dwordx4 v[12:15], v[28:29] offset:1024
	s_nop 0
	flat_load_dwordx4 v[16:19], v[16:17]
	s_nop 0
	flat_load_dwordx4 v[20:23], v[20:21]
	s_nop 0
	flat_load_dwordx4 v[24:27], v[28:29] offset:2048
	s_nop 0
	flat_load_dwordx4 v[28:31], v[28:29] offset:3072
	s_mov_b32 s4, 0x400000
	v_add_co_u32_e32 v42, vcc, s4, v42
	s_and_b64 s[4:5], s[12:13], exec
	s_nop 0
	v_addc_co_u32_e32 v43, vcc, 0, v43, vcc
	global_load_dword v133, v[42:43], off
	s_cselect_b32 s14, s1, s7
	s_cselect_b32 s15, s0, s6
	v_lshl_add_u64 v[42:43], s[16:17], 0, v[96:97]
	s_mov_b64 s[0:1], 0x102000
	v_lshl_add_u64 v[84:85], v[42:43], 0, s[0:1]
	s_mov_b64 s[0:1], 0x400040
	v_mov_b32_e32 v96, v97
	v_lshl_add_u64 v[86:87], v[40:41], 0, s[0:1]
	v_mov_b64_e32 v[56:57], v[96:97]
	v_mov_b64_e32 v[52:53], v[96:97]
	v_mov_b64_e32 v[36:37], v[96:97]
	v_mov_b64_e32 v[32:33], v[96:97]
	v_mov_b64_e32 v[72:73], v[96:97]
	v_mov_b64_e32 v[64:65], v[96:97]
	v_mov_b64_e32 v[48:49], v[96:97]
	v_mov_b64_e32 v[40:41], v[96:97]
	v_mov_b64_e32 v[76:77], v[96:97]
	v_mov_b64_e32 v[68:69], v[96:97]
	v_mov_b64_e32 v[60:61], v[96:97]
	v_mov_b64_e32 v[44:45], v[96:97]
	v_mov_b64_e32 v[58:59], v[98:99]
	v_mov_b64_e32 v[54:55], v[98:99]
	v_mov_b64_e32 v[38:39], v[98:99]
	v_mov_b64_e32 v[34:35], v[98:99]
	v_mov_b64_e32 v[74:75], v[98:99]
	v_mov_b64_e32 v[66:67], v[98:99]
	v_mov_b64_e32 v[50:51], v[98:99]
	v_mov_b64_e32 v[42:43], v[98:99]
	v_mov_b64_e32 v[78:79], v[98:99]
	v_mov_b64_e32 v[70:71], v[98:99]
	v_mov_b64_e32 v[62:63], v[98:99]
	v_mov_b64_e32 v[46:47], v[98:99]
	s_waitcnt vmcnt(0)
	s_branch .LBB0_987
; DI unsigned pk2c(float lo, float hi) { unsigned r; asm("v_cvt_pk_bf16_f32 %0, %1, %2" : "=v"(r) : "v"(lo), "v"(hi)); return r; }
; DI float bflo(unsigned w) { return __uint_as_float(w << 16); }
; DI float bfhi(unsigned w) { return __uint_as_float(w & 0xffff0000u); }
; DI void rowpass(const Cx& a, int mode, int l, int tid, int gw, int NGW) {
;     ...
;                 float ss = sc_;
;                 ss += __shfl_xor(ss, 1); ss += __shfl_xor(ss, 2); ss += __shfl_xor(ss, 4); ss += __shfl_xor(ss, 8);
;                 const float rstd = rsqrtf(ss * (1.f / DM) + EPS);
; #pragma unroll
;                 for (int j = 0; j < 4; ++j) { f32x4 y, x; y[0] = bflo(yc[j].x); y[1] = bfhi(yc[j].x); y[2] = bflo(yc[j].y); y[3] = bfhi(yc[j].y);
;                     x[0] = bflo(xbc[j].x); x[1] = bfhi(xbc[j].x); x[2] = bflo(xbc[j].y); x[3] = bfhi(xbc[j].y);
;                     v[j] = x + gtv[j] * (y * rstd * gnv[j]); }
;             }
;             if (last) {
;                 float* op = a.out + ((size_t)b * SEQ + n) * DM;
; #pragma unroll
;                 for (int j = 0; j < 4; ++j) *(f32x4*)(op + 4 * lane + 256 * j) = v[j];
;             } else {
;                 bf16_t* xp = RP_XDST(b, n);
; #pragma unroll
;                 for (int j = 0; j < 4; ++j) { u32x2 w; w.x = pk2c(v[j][0], v[j][1]); w.y = pk2c(v[j][2], v[j][3]); *(u32x2*)(xp + 4 * lane + 256 * j) = w; }
;                 float s2 = 0.f;
; #pragma unroll
;                 for (int j = 0; j < 4; ++j) s2 += (v[j][0] * v[j][0] + v[j][1] * v[j][1]) + (v[j][2] * v[j][2] + v[j][3] * v[j][3]);
;                 const float rinv = rsqrtf(wave_sum(s2) * (1.f / DM) + EPS);
; #pragma unroll
;                 for (int j = 0; j < 4; ++j) { const f32x4 h = v[j] * rinv * g2v[j] * (1.f + scv[j]) + shv[j]; u32x2 w; w.x = pk2c(h[0], h[1]); w.y = pk2c(h[2], h[3]);
;                     *(u32x2*)(H + (size_t)row * DM + 4 * lane + 256 * j) = w; }
.LBB0_985:
	s_or_b64 exec, exec, s[26:27]
	v_and_b32_e32 v91, 64, v227
	v_xor_b32_e32 v93, 1, v227
	v_add_u32_e32 v91, 64, v91
	v_cmp_lt_i32_e64 s[0:1], v93, v91
	v_xor_b32_e32 v131, 2, v227
	v_lshlrev_b32_e32 v138, 16, v128
	v_cndmask_b32_e64 v93, v227, v93, s[0:1]
	v_lshlrev_b32_e32 v93, 2, v93
	ds_bpermute_b32 v130, v93, v133
	v_cmp_lt_i32_e64 s[0:1], v131, v91
	v_and_b32_e32 v139, 0xffff0000, v128
	v_lshlrev_b32_e32 v128, 16, v129
	v_cndmask_b32_e64 v131, v227, v131, s[0:1]
	s_waitcnt lgkmcnt(0)
	v_add_f32_e32 v130, v133, v130
	v_lshlrev_b32_e32 v142, 2, v131
	ds_bpermute_b32 v131, v142, v130
	v_and_b32_e32 v129, 0xffff0000, v129
	v_lshlrev_b32_e32 v140, 16, v126
	v_and_b32_e32 v141, 0xffff0000, v126
	v_lshlrev_b32_e32 v126, 16, v127
	s_waitcnt lgkmcnt(0)
	v_add_f32_e32 v130, v130, v131
	v_xor_b32_e32 v131, 4, v227
	v_cmp_lt_i32_e64 s[0:1], v131, v91
	v_and_b32_e32 v127, 0xffff0000, v127
	v_ashrrev_i32_e32 v133, 31, v132
	v_cndmask_b32_e64 v131, v227, v131, s[0:1]
	v_lshlrev_b32_e32 v143, 2, v131
	ds_bpermute_b32 v131, v143, v130
	v_ashrrev_i32_e32 v137, 31, v136
	v_cndmask_b32_e64 v137, v137, 0, vcc
	s_waitcnt lgkmcnt(0)
	v_add_f32_e32 v130, v130, v131
	v_xor_b32_e32 v131, 8, v227
	v_cmp_lt_i32_e64 s[0:1], v131, v91
	s_nop 1
	v_cndmask_b32_e64 v131, v227, v131, s[0:1]
	v_lshlrev_b32_e32 v144, 2, v131
	ds_bpermute_b32 v131, v144, v130
	s_waitcnt lgkmcnt(0)
	v_add_f32_e32 v130, v130, v131
	v_fmamk_f32 v130, v130, 0x3a800000, v228
	v_cmp_gt_f32_e64 s[0:1], s39, v130
	v_mul_f32_e32 v131, 0x4b800000, v130
	s_nop 0
	v_cndmask_b32_e64 v130, v130, v131, s[0:1]
	v_rsq_f32_e32 v130, v130
	s_nop 0
	v_mul_f32_e32 v131, 0x45800000, v130
	v_cndmask_b32_e64 v130, v130, v131, s[0:1]
	v_pk_mul_f32 v[128:129], v[130:131], v[128:129] op_sel_hi:[0,1]
	v_pk_mul_f32 v[138:139], v[130:131], v[138:139] op_sel_hi:[0,1]
	v_pk_mul_f32 v[138:139], v[8:9], v[138:139]
	v_pk_mul_f32 v[128:129], v[10:11], v[128:129]
	s_mov_b32 s0, 0x3a00000
	v_pk_fma_f32 v[126:127], v[34:35], v[128:129], v[126:127]
	v_pk_fma_f32 v[128:129], v[32:33], v[138:139], v[140:141]
	v_lshlrev_b32_e32 v138, 16, v124
	v_and_b32_e32 v139, 0xffff0000, v124
	v_lshlrev_b32_e32 v124, 16, v125
	v_and_b32_e32 v125, 0xffff0000, v125
	v_pk_mul_f32 v[124:125], v[130:131], v[124:125] op_sel_hi:[0,1]
	v_pk_mul_f32 v[138:139], v[130:131], v[138:139] op_sel_hi:[0,1]
	v_lshlrev_b32_e32 v140, 16, v122
	v_and_b32_e32 v141, 0xffff0000, v122
	v_lshlrev_b32_e32 v122, 16, v123
	v_and_b32_e32 v123, 0xffff0000, v123
	v_pk_mul_f32 v[138:139], v[4:5], v[138:139]
	v_pk_mul_f32 v[124:125], v[6:7], v[124:125]
	s_nop 0
	v_pk_fma_f32 v[122:123], v[38:39], v[124:125], v[122:123]
	v_pk_fma_f32 v[124:125], v[36:37], v[138:139], v[140:141]
	v_lshlrev_b32_e32 v138, 16, v120
	v_and_b32_e32 v139, 0xffff0000, v120
	v_lshlrev_b32_e32 v120, 16, v121
	v_and_b32_e32 v121, 0xffff0000, v121
	v_pk_mul_f32 v[120:121], v[130:131], v[120:121] op_sel_hi:[0,1]
	v_pk_mul_f32 v[138:139], v[130:131], v[138:139] op_sel_hi:[0,1]
	v_lshlrev_b32_e32 v140, 16, v118
	v_and_b32_e32 v141, 0xffff0000, v118
	v_lshlrev_b32_e32 v118, 16, v119
	v_and_b32_e32 v119, 0xffff0000, v119
	v_pk_mul_f32 v[138:139], v[16:17], v[138:139]
	v_pk_mul_f32 v[120:121], v[18:19], v[120:121]
	s_nop 0
	v_pk_fma_f32 v[118:119], v[54:55], v[120:121], v[118:119]
	v_pk_fma_f32 v[120:121], v[52:53], v[138:139], v[140:141]
	v_lshlrev_b32_e32 v138, 16, v116
	v_and_b32_e32 v139, 0xffff0000, v116
	v_lshlrev_b32_e32 v116, 16, v117
	v_and_b32_e32 v117, 0xffff0000, v117
	v_pk_mul_f32 v[116:117], v[130:131], v[116:117] op_sel_hi:[0,1]
	v_pk_mul_f32 v[130:131], v[130:131], v[138:139] op_sel_hi:[0,1]
	v_lshlrev_b32_e32 v140, 16, v114
	v_and_b32_e32 v141, 0xffff0000, v114
	v_lshlrev_b32_e32 v114, 16, v115
	v_and_b32_e32 v115, 0xffff0000, v115
	v_pk_mul_f32 v[130:131], v[20:21], v[130:131]
	v_pk_mul_f32 v[116:117], v[22:23], v[116:117]
	v_add_u32_e32 v138, 0xfffff000, v136
	v_pk_fma_f32 v[114:115], v[58:59], v[116:117], v[114:115]
	v_pk_fma_f32 v[116:117], v[56:57], v[130:131], v[140:141]
	v_mov_b32_e32 v130, s14
	v_mov_b32_e32 v131, s10
	v_cndmask_b32_e32 v131, v130, v131, vcc
	v_mov_b32_e32 v130, s15
	v_mov_b32_e32 v139, s9
	v_cndmask_b32_e32 v136, v136, v138, vcc
	v_cndmask_b32_e64 v138, 23, 19, vcc
	v_cndmask_b32_e32 v130, v130, v139, vcc
	v_lshlrev_b64 v[132:133], v138, v[132:133]
	v_lshl_add_u64 v[130:131], v[130:131], 0, v[132:133]
	v_lshlrev_b64 v[132:133], 11, v[136:137]
	v_lshl_add_u64 v[130:131], v[130:131], 0, v[132:133]
	v_lshl_add_u64 v[130:131], v[130:131], 0, v[96:97]
	v_cvt_pk_bf16_f32 v132, v128, v129
	v_cvt_pk_bf16_f32 v133, v126, v127
	global_store_dwordx2 v[130:131], v[132:133], off
	v_cvt_pk_bf16_f32 v132, v124, v125
	v_cvt_pk_bf16_f32 v133, v122, v123
	global_store_dwordx2 v[130:131], v[132:133], off offset:512
	v_cvt_pk_bf16_f32 v132, v120, v121
	v_cvt_pk_bf16_f32 v133, v118, v119
	global_store_dwordx2 v[130:131], v[132:133], off offset:1024
	v_cvt_pk_bf16_f32 v132, v116, v117
	v_cvt_pk_bf16_f32 v133, v114, v115
	global_store_dwordx2 v[130:131], v[132:133], off offset:1536
	v_pk_mul_f32 v[130:131], v[126:127], v[126:127]
	v_pk_mul_f32 v[132:133], v[128:129], v[128:129]
	v_mul_f32_e32 v96, v120, v120
	v_pk_mov_b32 v[136:137], v[132:133], v[130:131] op_sel:[1,0]
	v_mov_b32_e32 v133, v131
	v_pk_add_f32 v[130:131], v[136:137], v[132:133]
	v_pk_mul_f32 v[132:133], v[122:123], v[122:123]
	v_pk_mul_f32 v[136:137], v[124:125], v[124:125]
	v_pk_add_f32 v[130:131], v[130:131], v[130:131] op_sel_hi:[0,1]
	v_pk_mov_b32 v[138:139], v[136:137], v[132:133] op_sel:[1,0]
	v_mov_b32_e32 v137, v133
	v_pk_add_f32 v[132:133], v[138:139], v[136:137]
	v_pk_fma_f32 v[136:137], v[120:121], v[120:121], v[96:97] op_sel_hi:[1,1,0]
	v_mul_f32_e32 v96, v118, v118
	v_pk_add_f32 v[132:133], v[132:133], v[132:133] op_sel_hi:[0,1]
	v_pk_fma_f32 v[138:139], v[118:119], v[118:119], v[96:97] op_sel_hi:[1,1,0]
	v_mul_f32_e32 v136, v116, v116
	v_mul_f32_e32 v138, v117, v117
	v_mul_f32_e32 v130, v114, v114
	v_mul_f32_e32 v132, v115, v115
	v_pk_add_f32 v[136:137], v[136:137], v[138:139]
	v_pk_add_f32 v[130:131], v[130:131], v[132:133]
	v_pk_add_f32 v[132:133], v[44:45], 1.0 op_sel_hi:[1,0]
	v_pk_add_f32 v[130:131], v[136:137], v[130:131]
	s_nop 0
	v_add_f32_e32 v96, v130, v131
	ds_bpermute_b32 v93, v93, v96
	v_pk_add_f32 v[130:131], v[46:47], 1.0 op_sel_hi:[1,0]
	s_waitcnt lgkmcnt(0)
; DI unsigned pk2c(float lo, float hi) { unsigned r; asm("v_cvt_pk_bf16_f32 %0, %1, %2" : "=v"(r) : "v"(lo), "v"(hi)); return r; }
; DI void rowpass(const Cx& a, int mode, int l, int tid, int gw, int NGW) {
;     ...
;                 float s2 = 0.f;
; #pragma unroll
;                 for (int j = 0; j < 4; ++j) s2 += (v[j][0] * v[j][0] + v[j][1] * v[j][1]) + (v[j][2] * v[j][2] + v[j][3] * v[j][3]);
;                 const float rinv = rsqrtf(wave_sum(s2) * (1.f / DM) + EPS);
; #pragma unroll
;                 for (int j = 0; j < 4; ++j) { const f32x4 h = v[j] * rinv * g2v[j] * (1.f + scv[j]) + shv[j]; u32x2 w; w.x = pk2c(h[0], h[1]); w.y = pk2c(h[2], h[3]);
;                     *(u32x2*)(H + (size_t)row * DM + 4 * lane + 256 * j) = w; }
;             }
;         }
; #pragma unroll
;         for (int j = 0; j < 4; ++j) { xfc[j] = xfn[j]; xbc[j] = xbn[j]; yc[j] = yn[j]; }
;         sc_ = sn_;
	v_add_f32_e32 v93, v96, v93
	ds_bpermute_b32 v96, v142, v93
	s_waitcnt lgkmcnt(0)
	v_add_f32_e32 v93, v93, v96
	ds_bpermute_b32 v96, v143, v93
	s_waitcnt lgkmcnt(0)
	v_add_f32_e32 v93, v93, v96
	ds_bpermute_b32 v96, v144, v93
	s_waitcnt lgkmcnt(0)
	v_add_f32_e32 v93, v93, v96
	v_xor_b32_e32 v96, 16, v227
	v_cmp_lt_i32_e32 vcc, v96, v91
	s_nop 1
	v_cndmask_b32_e32 v96, v227, v96, vcc
	v_lshlrev_b32_e32 v96, 2, v96
	ds_bpermute_b32 v96, v96, v93
	s_waitcnt lgkmcnt(0)
	v_add_f32_e32 v93, v93, v96
	v_xor_b32_e32 v96, 32, v227
	v_cmp_lt_i32_e32 vcc, v96, v91
	s_nop 1
	v_cndmask_b32_e32 v91, v227, v96, vcc
	v_lshlrev_b32_e32 v91, 2, v91
	ds_bpermute_b32 v91, v91, v93
	s_waitcnt lgkmcnt(0)
	v_add_f32_e32 v91, v93, v91
	v_fmamk_f32 v91, v91, 0x3a800000, v228
	v_cmp_gt_f32_e32 vcc, s39, v91
	v_mul_f32_e32 v93, 0x4b800000, v91
	s_nop 0
	v_cndmask_b32_e32 v91, v91, v93, vcc
	v_rsq_f32_e32 v91, v91
	s_nop 0
	v_mul_f32_e32 v93, 0x45800000, v91
	v_cndmask_b32_e32 v96, v91, v93, vcc
	v_pk_mul_f32 v[128:129], v[128:129], v[96:97] op_sel_hi:[1,0]
	v_pk_mul_f32 v[126:127], v[126:127], v[96:97] op_sel_hi:[1,0]
	v_pk_mul_f32 v[128:129], v[0:1], v[128:129]
	v_pk_mul_f32 v[126:127], v[2:3], v[126:127]
	v_pk_fma_f32 v[128:129], v[132:133], v[128:129], v[40:41]
	v_add_co_u32_e32 v112, vcc, s0, v112
	v_pk_fma_f32 v[126:127], v[130:131], v[126:127], v[42:43]
	v_cvt_pk_bf16_f32 v128, v128, v129
	s_nop 0
	v_addc_co_u32_e32 v113, vcc, 0, v113, vcc
	v_cvt_pk_bf16_f32 v129, v126, v127
	v_pk_mul_f32 v[124:125], v[124:125], v[96:97] op_sel_hi:[1,0]
	global_store_dwordx2 v[112:113], v[128:129], off
	v_pk_mul_f32 v[122:123], v[122:123], v[96:97] op_sel_hi:[1,0]
	v_pk_mul_f32 v[124:125], v[12:13], v[124:125]
	v_pk_add_f32 v[128:129], v[60:61], 1.0 op_sel_hi:[1,0]
	v_pk_mul_f32 v[122:123], v[14:15], v[122:123]
	v_pk_add_f32 v[126:127], v[62:63], 1.0 op_sel_hi:[1,0]
	v_pk_fma_f32 v[124:125], v[128:129], v[124:125], v[48:49]
	v_pk_fma_f32 v[122:123], v[126:127], v[122:123], v[50:51]
	v_cvt_pk_bf16_f32 v124, v124, v125
	v_pk_mul_f32 v[120:121], v[120:121], v[96:97] op_sel_hi:[1,0]
	v_cvt_pk_bf16_f32 v125, v122, v123
	global_store_dwordx2 v[112:113], v[124:125], off offset:512
	v_pk_mul_f32 v[118:119], v[118:119], v[96:97] op_sel_hi:[1,0]
	v_pk_mul_f32 v[120:121], v[24:25], v[120:121]
	v_pk_add_f32 v[124:125], v[68:69], 1.0 op_sel_hi:[1,0]
	v_pk_mul_f32 v[118:119], v[26:27], v[118:119]
	v_pk_add_f32 v[122:123], v[70:71], 1.0 op_sel_hi:[1,0]
	v_pk_fma_f32 v[120:121], v[124:125], v[120:121], v[64:65]
	v_pk_fma_f32 v[118:119], v[122:123], v[118:119], v[66:67]
	v_cvt_pk_bf16_f32 v120, v120, v121
	v_pk_mul_f32 v[116:117], v[116:117], v[96:97] op_sel_hi:[1,0]
	v_cvt_pk_bf16_f32 v121, v118, v119
	global_store_dwordx2 v[112:113], v[120:121], off offset:1024
	v_pk_mul_f32 v[114:115], v[114:115], v[96:97] op_sel_hi:[1,0]
	v_pk_mul_f32 v[116:117], v[28:29], v[116:117]
	v_pk_add_f32 v[120:121], v[76:77], 1.0 op_sel_hi:[1,0]
	v_pk_mul_f32 v[114:115], v[30:31], v[114:115]
	v_pk_add_f32 v[118:119], v[78:79], 1.0 op_sel_hi:[1,0]
	v_pk_fma_f32 v[116:117], v[120:121], v[116:117], v[72:73]
	v_pk_fma_f32 v[114:115], v[118:119], v[114:115], v[74:75]
	v_cvt_pk_bf16_f32 v116, v116, v117
	s_nop 0
	v_cvt_pk_bf16_f32 v117, v114, v115
	global_store_dwordx2 v[112:113], v[116:117], off offset:1536
	s_waitcnt vmcnt(8)
.LBB0_986:
	s_or_b64 exec, exec, s[24:25]
	s_and_b64 s[0:1], exec, s[4:5]
	s_or_b64 s[22:23], s[0:1], s[22:23]
	v_lshl_add_u64 v[82:83], v[82:83], 0, s[64:65]
	v_lshl_add_u64 v[86:87], v[86:87], 0, 64
	v_mov_b32_e32 v133, v134
	v_mov_b32_e32 v130, v135
	v_mov_b32_e32 v126, v94
	v_mov_b32_e32 v127, v95
	v_mov_b32_e32 v122, v98
	v_mov_b32_e32 v123, v99
	v_mov_b32_e32 v118, v100
	v_mov_b32_e32 v119, v101
	v_mov_b32_e32 v114, v102
	v_mov_b32_e32 v115, v103
	v_mov_b32_e32 v128, v110
	v_mov_b32_e32 v129, v111
	v_mov_b32_e32 v124, v108
	v_mov_b32_e32 v125, v109
	v_mov_b32_e32 v120, v106
	v_mov_b32_e32 v121, v107
	v_mov_b32_e32 v116, v104
	v_mov_b32_e32 v117, v105
	s_andn2_b64 exec, exec, s[22:23]
	s_cbranch_execz .LBB0_992

; DI void rowpass(const Cx& a, int mode, int l, int tid, int gw, int NGW) {
;     ...
;     for (int row = r0; row < r1; ++row) {
;         if (row + 1 < r1) RP_LOAD(row + 1, xfn, xbn, yn, sn_);
;         const int b = row / NB, n = row - b * NB; const bool lat = n < SEQ; const int mv = lat ? b : 16;
;         if (!(skipc && !lat)) {
;             if (mv != cur_mv) { cur_mv = mv;
;                 const float* mb = MOD + ((size_t)l * NMOD + mv) * MODW; const float* mb2 = MOD + ((size_t)l2 * NMOD + mv) * MODW;
; #pragma unroll
;                 for (int j = 0; j < 4; ++j) { const int c = 4 * lane + 256 * j;
;                     if (mode != 0) gtv[j] = *(const f32x4*)(mb + (mode == 1 ? 2 * DM : 5 * DM) + c);
;                     if (!last) { shv[j] = *(const f32x4*)(mb2 + (mode == 1 ? 3 * DM : 0) + c); scv[j] = *(const f32x4*)(mb2 + (mode == 1 ? 4 * DM : DM) + c); } } }
.LBB0_989:
	s_or_b64 exec, exec, s[0:1]
	v_mul_hi_i32 v91, v130, s59
	v_lshrrev_b32_e32 v93, 31, v91
	v_ashrrev_i32_e32 v91, 11, v91
	v_add_u32_e32 v132, v91, v93
	v_mad_i32_i24 v136, v132, s51, v130
	v_cmp_lt_i32_e32 vcc, s50, v136
	s_and_b64 s[0:1], s[12:13], vcc
	s_xor_b64 s[0:1], s[0:1], -1
	s_and_saveexec_b64 s[24:25], s[0:1]
	s_cbranch_execz .Lrp1_skip
	v_cndmask_b32_e64 v130, v132, 16, vcc
	v_cmp_ne_u32_e64 s[0:1], v130, v89
	s_and_saveexec_b64 s[26:27], s[0:1]
	s_cbranch_execz .LBB0_985
	v_ashrrev_i32_e32 v131, 31, v130
	v_lshl_add_u64 v[32:33], s[52:53], 0, v[130:131]
	v_mov_b64_e32 v[34:35], s[20:21]
	s_movk_i32 s28, 0x6000
	v_mad_u64_u32 v[34:35], s[0:1], v32, s28, v[34:35]
	v_mad_i32_i24 v35, v33, s28, v35
	s_mov_b64 s[0:1], 0x3000
	v_lshl_add_u64 v[72:73], v[34:35], 0, s[0:1]
	s_mov_b64 s[0:1], 0x4000
	v_lshl_add_u64 v[74:75], v[34:35], 0, s[0:1]
	v_mad_u64_u32 v[56:57], s[0:1], v32, s28, v[84:85]
	v_mad_i32_i24 v57, v33, s28, v57
	v_lshlrev_b32_e32 v32, 2, v80
	v_mov_b32_e32 v33, v97
	v_mov_b32_e32 v89, v97
	v_lshl_add_u64 v[34:35], v[74:75], 0, v[32:33]
	v_lshl_add_u64 v[32:33], v[72:73], 0, v[32:33]
	v_lshl_add_u64 v[52:53], v[74:75], 0, v[88:89]
	v_lshl_add_u64 v[48:49], v[72:73], 0, v[88:89]
	v_mov_b32_e32 v91, v97
	global_load_dwordx4 v[40:43], v[32:33], off
	global_load_dwordx4 v[44:47], v[34:35], off
	s_nop 0
	global_load_dwordx4 v[32:35], v[56:57], off
	global_load_dwordx4 v[36:39], v[56:57], off offset:1024
	s_nop 0
	global_load_dwordx4 v[48:51], v[48:49], off
	s_nop 0
	global_load_dwordx4 v[60:63], v[52:53], off
	v_lshl_add_u64 v[52:53], v[74:75], 0, v[90:91]
	v_lshl_add_u64 v[54:55], v[72:73], 0, v[90:91]
	global_load_dwordx4 v[64:67], v[54:55], off
	global_load_dwordx4 v[68:71], v[52:53], off
	s_nop 0
	global_load_dwordx4 v[52:55], v[56:57], off offset:2048
	s_nop 0
	global_load_dwordx4 v[56:59], v[56:57], off offset:3072
	v_mov_b32_e32 v93, v97
	v_lshl_add_u64 v[76:77], v[74:75], 0, v[92:93]
	v_lshl_add_u64 v[72:73], v[72:73], 0, v[92:93]
	global_load_dwordx4 v[72:75], v[72:73], off
	s_nop 0
	global_load_dwordx4 v[76:79], v[76:77], off
	v_mov_b32_e32 v89, v130
	s_waitcnt vmcnt(0)
	s_branch .LBB0_985

; DI void rowpass(const Cx& a, int mode, int l, int tid, int gw, int NGW) {
;     ...
;     const int chunk = (ROWS + NGW - 1) / NGW; const int r0 = gw * chunk; const int r1 = (r0 + chunk < ROWS) ? r0 + chunk : ROWS;
;     if (r0 >= r1) return;
;     const bool lastl = (l == DEPTH - 1);
;     const bool last = (mode == 2 && lastl);
;     const bool skipc = (mode != 0 && lastl);
;     const int l2 = (mode == 2) ? l + 1 : l; const int k2 = (mode == 1) ? 2 : 0;
;     f32x4 gnv[4], g2v[4], gtv[4], shv[4], scv[4];
; #pragma unroll
;     for (int j = 0; j < 4; ++j) { const int c = 4 * lane + 256 * j;
;         gnv[j] = (mode == 0) ? (f32x4){0.f, 0.f, 0.f, 0.f} : *(const f32x4*)(normg + ((size_t)l * 4 + (mode == 1 ? 1 : 3)) * DM + c);
;         g2v[j] = last ? (f32x4){0.f, 0.f, 0.f, 0.f} : *(const f32x4*)(normg + ((size_t)l2 * 4 + k2) * DM + c);
;         gtv[j] = (f32x4){0.f, 0.f, 0.f, 0.f}; shv[j] = gtv[j]; scv[j] = gtv[j]; }
;     int cur_mv = -1;
;     f32x4 xfc[4], xfn[4]; u32x2 xbc[4], xbn[4]; u32x2 yc[4], yn[4]; float sc_ = 0.f, sn_ = 0.f;
;     ...
;     RP_LOAD(r0, xfc, xbc, yc, sc_);
;     ...
; #pragma unroll
;         for (int j = 0; j < 4; ++j) { xfc[j] = xfn[j]; xbc[j] = xbn[j]; yc[j] = yn[j]; }
;         sc_ = sn_;
.LBB0_1267:
	v_mul_hi_i32 v32, v80, s59
	s_add_u32 s18, s8, 0x2a00000
	v_lshrrev_b32_e32 v33, 31, v32
	v_ashrrev_i32_e32 v32, 11, v32
	s_addc_u32 s19, s9, 0
	v_add_u32_e32 v36, v32, v33
	s_add_u32 s6, s8, 0x25200000
	v_mad_i32_i24 v32, v36, s51, v80
	s_addc_u32 s7, s9, 0
	v_cmp_lt_i32_e32 vcc, s50, v32
	v_ashrrev_i32_e32 v37, 31, v36
	s_and_saveexec_b64 s[4:5], vcc
	s_xor_b64 s[4:5], exec, s[4:5]
	s_and_b64 s[14:15], s[12:13], exec
	v_add_u32_e32 v96, 0xfffff000, v32
	v_lshlrev_b64 v[32:33], 19, v[36:37]
	s_cselect_b32 s15, s7, s1
	s_cselect_b32 s14, s6, s0
	v_lshl_add_u64 v[34:35], s[18:19], 0, v[32:33]
	v_mov_b64_e32 v[106:107], s[14:15]
	v_mov_b64_e32 v[32:33], v[96:97]
	s_andn2_saveexec_b64 s[4:5], s[4:5]
	s_and_b64 s[14:15], s[12:13], exec
	s_cselect_b32 s7, s7, s1
	s_cselect_b32 s6, s6, s0
	v_lshlrev_b64 v[34:35], 23, v[36:37]
	v_ashrrev_i32_e32 v33, 31, v32
	v_lshl_add_u64 v[34:35], s[6:7], 0, v[34:35]
	v_mov_b64_e32 v[106:107], s[6:7]
	s_or_b64 exec, exec, s[4:5]
	v_ashrrev_i32_e32 v81, 31, v80
	v_lshlrev_b64 v[32:33], 11, v[32:33]
	v_lshlrev_b64 v[108:109], 11, v[80:81]
	v_lshl_add_u64 v[32:33], v[34:35], 0, v[32:33]
	v_lshlrev_b32_e32 v96, 1, v40
	v_lshl_add_u64 v[34:35], s[8:9], 0, v[108:109]
	v_lshl_add_u64 v[34:35], v[34:35], 0, v[96:97]
	s_mov_b64 s[4:5], 0x3a00000
	v_lshl_add_u64 v[36:37], v[34:35], 0, s[4:5]
	s_mov_b32 s4, 0x3a00000
	v_lshl_add_u64 v[32:33], v[32:33], 0, v[96:97]
	v_add_co_u32_e32 v34, vcc, s4, v34
	s_mov_b32 s4, 0x400000
	s_nop 0
	v_addc_co_u32_e32 v35, vcc, 0, v35, vcc
	global_load_dwordx2 v[82:83], v[32:33], off
	global_load_dwordx2 v[84:85], v[32:33], off offset:512
	global_load_dwordx2 v[88:89], v[32:33], off offset:1024
	global_load_dwordx2 v[92:93], v[32:33], off offset:1536
	global_load_dwordx2 v[136:137], v[34:35], off
	global_load_dwordx2 v[86:87], v[36:37], off offset:512
	global_load_dwordx2 v[90:91], v[36:37], off offset:1024
	global_load_dwordx2 v[94:95], v[36:37], off offset:1536
	v_lshlrev_b64 v[32:33], 6, v[80:81]
	v_lshl_add_u64 v[32:33], s[8:9], 0, v[32:33]
	v_and_b32_e32 v34, 60, v39
	v_mov_b32_e32 v35, v97
	v_lshl_add_u64 v[32:33], v[32:33], 0, v[34:35]
	v_add_co_u32_e32 v32, vcc, s4, v32
	v_readlane_b32 s4, v248, 29
	s_nop 0
	v_addc_co_u32_e32 v33, vcc, 0, v33, vcc
	global_load_dword v133, v[32:33], off
	v_readlane_b32 s5, v248, 30
	v_mov_b32_e32 v99, v97
	s_mul_hi_u32 s23, s4, 17
	s_mul_i32 s22, s4, 17
	v_lshl_add_u64 v[32:33], s[8:9], 0, v[98:99]
	s_mov_b64 s[4:5], 0x105000
	v_lshl_add_u64 v[110:111], v[32:33], 0, s[4:5]
	v_lshlrev_b32_e32 v32, 3, v38
	v_and_b32_e32 v35, 0x1f8, v32
	v_add_u32_e32 v32, 1, v80
	v_ashrrev_i32_e32 v33, 31, v32
	v_lshlrev_b64 v[36:37], 6, v[32:33]
	v_or_b32_e32 v36, v36, v34
	s_mov_b64 s[4:5], 0x400000
	v_lshlrev_b64 v[114:115], 11, v[32:33]
	v_mov_b32_e32 v76, v97
	v_mov_b32_e32 v77, v97
	s_add_u32 s20, s8, 0x100000
	v_or_b32_e32 v108, v108, v35
	v_lshl_add_u64 v[112:113], v[36:37], 0, s[4:5]
	v_or_b32_e32 v114, v114, v35
	v_mov_b32_e32 v78, v97
	v_mov_b32_e32 v79, v97
	v_mov_b64_e32 v[72:73], v[76:77]
	v_mov_b64_e32 v[68:69], v[76:77]
	v_mov_b64_e32 v[64:65], v[76:77]
	v_mov_b64_e32 v[32:33], v[76:77]
	v_mov_b64_e32 v[40:41], v[76:77]
	v_mov_b64_e32 v[44:45], v[76:77]
	v_mov_b64_e32 v[36:37], v[76:77]
	v_mov_b64_e32 v[48:49], v[76:77]
	v_mov_b64_e32 v[56:57], v[76:77]
	v_mov_b64_e32 v[60:61], v[76:77]
	v_mov_b64_e32 v[52:53], v[76:77]
	s_addc_u32 s21, s9, 0
	v_mov_b32_e32 v143, 0
	v_mov_b32_e32 v101, -1
	s_mov_b64 s[24:25], 0
	v_mov_b64_e32 v[74:75], v[78:79]
	v_mov_b64_e32 v[70:71], v[78:79]
	v_mov_b64_e32 v[66:67], v[78:79]
	v_mov_b64_e32 v[34:35], v[78:79]
	v_mov_b64_e32 v[42:43], v[78:79]
	v_mov_b64_e32 v[46:47], v[78:79]
	v_mov_b64_e32 v[38:39], v[78:79]
	v_mov_b64_e32 v[50:51], v[78:79]
	v_mov_b64_e32 v[58:59], v[78:79]
	v_mov_b64_e32 v[62:63], v[78:79]
	v_mov_b64_e32 v[54:55], v[78:79]
	s_waitcnt vmcnt(0)
	s_branch .LBB0_1273
.LBB0_1272:
	s_or_b64 exec, exec, s[26:27]
	s_and_b64 s[4:5], exec, s[4:5]
	s_or_b64 s[24:25], s[4:5], s[24:25]
	s_mov_b64 s[4:5], 0x800
	v_lshl_add_u64 v[108:109], v[108:109], 0, s[4:5]
	v_lshl_add_u64 v[112:113], v[112:113], 0, 64
	s_mov_b64 s[64:65], 0x800
	v_lshl_add_u64 v[114:115], v[114:115], 0, s[4:5]
	v_mov_b32_e32 v133, v143
	v_mov_b32_e32 v80, v144
	v_mov_b32_e32 v82, v116
	v_mov_b32_e32 v83, v117
	v_mov_b32_e32 v84, v118
	v_mov_b32_e32 v85, v119
	v_mov_b32_e32 v88, v120
	v_mov_b32_e32 v89, v121
	v_mov_b32_e32 v92, v122
	v_mov_b32_e32 v93, v123
	v_mov_b32_e32 v136, v130
	v_mov_b32_e32 v137, v131
	v_mov_b32_e32 v86, v128
	v_mov_b32_e32 v87, v129
	v_mov_b32_e32 v90, v126
	v_mov_b32_e32 v91, v127
	v_mov_b32_e32 v94, v124
	v_mov_b32_e32 v95, v125
	s_andn2_b64 exec, exec, s[24:25]
	s_cbranch_execz .LBB0_1290

; DI float bflo(unsigned w) { return __uint_as_float(w << 16); }
; DI float bfhi(unsigned w) { return __uint_as_float(w & 0xffff0000u); }
; DI void rowpass(const Cx& a, int mode, int l, int tid, int gw, int NGW) {
;     ...
;             if (mv != cur_mv) { cur_mv = mv;
;                 const float* mb = MOD + ((size_t)l * NMOD + mv) * MODW; const float* mb2 = MOD + ((size_t)l2 * NMOD + mv) * MODW;
; #pragma unroll
;                 for (int j = 0; j < 4; ++j) { const int c = 4 * lane + 256 * j;
;                     if (mode != 0) gtv[j] = *(const f32x4*)(mb + (mode == 1 ? 2 * DM : 5 * DM) + c);
;                     if (!last) { shv[j] = *(const f32x4*)(mb2 + (mode == 1 ? 3 * DM : 0) + c); scv[j] = *(const f32x4*)(mb2 + (mode == 1 ? 4 * DM : DM) + c); } } }
;             f32x4 v[4];
;             if (mode == 0) {
; #pragma unroll
;                 for (int j = 0; j < 4; ++j) v[j] = xfc[j];
;             } else {
;                 float ss = sc_;
;                 ss += __shfl_xor(ss, 1); ss += __shfl_xor(ss, 2); ss += __shfl_xor(ss, 4); ss += __shfl_xor(ss, 8);
;                 const float rstd = rsqrtf(ss * (1.f / DM) + EPS);
; #pragma unroll
;                 for (int j = 0; j < 4; ++j) { f32x4 y, x; y[0] = bflo(yc[j].x); y[1] = bfhi(yc[j].x); y[2] = bflo(yc[j].y); y[3] = bfhi(yc[j].y);
;                     x[0] = bflo(xbc[j].x); x[1] = bfhi(xbc[j].x); x[2] = bflo(xbc[j].y); x[3] = bfhi(xbc[j].y);
;                     v[j] = x + gtv[j] * (y * rstd * gnv[j]); }
;             }
;             if (last) {
.LBB0_1282:
	v_mov_b32_e32 v101, v80
	s_waitcnt vmcnt(0)
.LBB0_1283:
	s_or_b64 exec, exec, s[28:29]
	v_and_b32_e32 v81, 64, v227
	v_xor_b32_e32 v80, 1, v227
	v_add_u32_e32 v99, 64, v81
	v_cmp_lt_i32_e32 vcc, v80, v99
	v_xor_b32_e32 v81, 2, v227
	v_lshlrev_b32_e32 v146, 16, v82
	v_cndmask_b32_e32 v80, v227, v80, vcc
	v_lshlrev_b32_e32 v103, 2, v80
	ds_bpermute_b32 v80, v103, v133
	v_cmp_lt_i32_e32 vcc, v81, v99
	v_and_b32_e32 v147, 0xffff0000, v82
	v_lshlrev_b32_e32 v82, 16, v83
	v_cndmask_b32_e32 v81, v227, v81, vcc
	s_waitcnt lgkmcnt(0)
	v_add_f32_e32 v80, v133, v80
	v_lshlrev_b32_e32 v105, 2, v81
	ds_bpermute_b32 v81, v105, v80
	v_xor_b32_e32 v133, 4, v227
	v_cmp_lt_i32_e32 vcc, v133, v99
	v_and_b32_e32 v83, 0xffff0000, v83
	v_readlane_b32 s14, v248, 23
	s_waitcnt lgkmcnt(0)
	v_add_f32_e32 v80, v80, v81
	v_cndmask_b32_e32 v81, v227, v133, vcc
	v_lshlrev_b32_e32 v138, 2, v81
	ds_bpermute_b32 v81, v138, v80
	v_xor_b32_e32 v133, 8, v227
	v_cmp_lt_i32_e32 vcc, v133, v99
	v_readlane_b32 s15, v248, 24
	s_mov_b64 s[28:29], -1
	s_waitcnt lgkmcnt(0)
	v_add_f32_e32 v81, v80, v81
	v_cndmask_b32_e32 v80, v227, v133, vcc
	v_lshlrev_b32_e32 v139, 2, v80
	ds_bpermute_b32 v133, v139, v81
	v_lshlrev_b32_e32 v80, 16, v136
	s_waitcnt lgkmcnt(0)
	v_add_f32_e32 v81, v81, v133
	v_fmamk_f32 v81, v81, 0x3a800000, v228
	v_mul_f32_e32 v133, 0x4b800000, v81
	v_cmp_gt_f32_e32 vcc, s39, v81
	s_nop 1
	v_cndmask_b32_e32 v81, v81, v133, vcc
	v_rsq_f32_e32 v133, v81
	v_and_b32_e32 v81, 0xffff0000, v136
	v_lshlrev_b32_e32 v136, 16, v137
	v_and_b32_e32 v137, 0xffff0000, v137
	v_mul_f32_e32 v135, 0x45800000, v133
	v_cndmask_b32_e32 v140, v133, v135, vcc
	v_pk_mul_f32 v[136:137], v[140:141], v[136:137] op_sel_hi:[0,1]
	v_pk_mul_f32 v[136:137], v[2:3], v[136:137]
	v_pk_mul_f32 v[80:81], v[140:141], v[80:81] op_sel_hi:[0,1]
	v_pk_fma_f32 v[82:83], v[66:67], v[136:137], v[82:83]
	v_lshlrev_b32_e32 v136, 16, v86
	v_and_b32_e32 v137, 0xffff0000, v86
	v_lshlrev_b32_e32 v86, 16, v87
	v_and_b32_e32 v87, 0xffff0000, v87
	v_pk_mul_f32 v[80:81], v[0:1], v[80:81]
	v_pk_mul_f32 v[86:87], v[140:141], v[86:87] op_sel_hi:[0,1]
	v_pk_mul_f32 v[136:137], v[140:141], v[136:137] op_sel_hi:[0,1]
	v_pk_fma_f32 v[80:81], v[64:65], v[80:81], v[146:147]
	v_lshlrev_b32_e32 v146, 16, v84
	v_and_b32_e32 v147, 0xffff0000, v84
	v_lshlrev_b32_e32 v84, 16, v85
	v_and_b32_e32 v85, 0xffff0000, v85
	v_pk_mul_f32 v[136:137], v[12:13], v[136:137]
	v_pk_mul_f32 v[86:87], v[14:15], v[86:87]
	v_ashrrev_i32_e32 v135, 31, v134
	v_pk_fma_f32 v[86:87], v[70:71], v[86:87], v[84:85]
	v_pk_fma_f32 v[84:85], v[68:69], v[136:137], v[146:147]
	v_lshlrev_b32_e32 v136, 16, v90
	v_and_b32_e32 v137, 0xffff0000, v90
	v_lshlrev_b32_e32 v90, 16, v91
	v_and_b32_e32 v91, 0xffff0000, v91
	v_pk_mul_f32 v[90:91], v[140:141], v[90:91] op_sel_hi:[0,1]
	v_pk_mul_f32 v[136:137], v[140:141], v[136:137] op_sel_hi:[0,1]
	v_lshlrev_b32_e32 v146, 16, v88
	v_and_b32_e32 v147, 0xffff0000, v88
	v_lshlrev_b32_e32 v88, 16, v89
	v_and_b32_e32 v89, 0xffff0000, v89
	v_pk_mul_f32 v[136:137], v[16:17], v[136:137]
	v_pk_mul_f32 v[90:91], v[18:19], v[90:91]
	s_and_b64 vcc, exec, s[14:15]
	v_pk_fma_f32 v[90:91], v[74:75], v[90:91], v[88:89]
	v_pk_fma_f32 v[88:89], v[72:73], v[136:137], v[146:147]
	v_lshlrev_b32_e32 v136, 16, v94
	v_and_b32_e32 v137, 0xffff0000, v94
	v_lshlrev_b32_e32 v94, 16, v95
	v_and_b32_e32 v95, 0xffff0000, v95
	v_pk_mul_f32 v[94:95], v[140:141], v[94:95] op_sel_hi:[0,1]
	v_pk_mul_f32 v[136:137], v[140:141], v[136:137] op_sel_hi:[0,1]
	v_lshlrev_b32_e32 v146, 16, v92
	v_and_b32_e32 v147, 0xffff0000, v92
	v_lshlrev_b32_e32 v92, 16, v93
	v_and_b32_e32 v93, 0xffff0000, v93
	v_pk_mul_f32 v[136:137], v[28:29], v[136:137]
	v_pk_mul_f32 v[94:95], v[30:31], v[94:95]
	v_ashrrev_i32_e32 v133, 31, v132
	v_pk_fma_f32 v[94:95], v[78:79], v[94:95], v[92:93]
	v_pk_fma_f32 v[92:93], v[76:77], v[136:137], v[146:147]
	s_cbranch_vccz .LBB0_1285
; DI unsigned pk2c(float lo, float hi) { unsigned r; asm("v_cvt_pk_bf16_f32 %0, %1, %2" : "=v"(r) : "v"(lo), "v"(hi)); return r; }
; DI void rowpass(const Cx& a, int mode, int l, int tid, int gw, int NGW) {
;     ...
;             if (last) {
;                 float* op = a.out + ((size_t)b * SEQ + n) * DM;
; #pragma unroll
;                 for (int j = 0; j < 4; ++j) *(f32x4*)(op + 4 * lane + 256 * j) = v[j];
;             } else {
;                 bf16_t* xp = RP_XDST(b, n);
; #pragma unroll
;                 for (int j = 0; j < 4; ++j) { u32x2 w; w.x = pk2c(v[j][0], v[j][1]); w.y = pk2c(v[j][2], v[j][3]); *(u32x2*)(xp + 4 * lane + 256 * j) = w; }
;                 float s2 = 0.f;
; #pragma unroll
;                 for (int j = 0; j < 4; ++j) s2 += (v[j][0] * v[j][0] + v[j][1] * v[j][1]) + (v[j][2] * v[j][2] + v[j][3] * v[j][3]);
;                 const float rinv = rsqrtf(wave_sum(s2) * (1.f / DM) + EPS);
; #pragma unroll
;                 for (int j = 0; j < 4; ++j) { const f32x4 h = v[j] * rinv * g2v[j] * (1.f + scv[j]) + shv[j]; u32x2 w; w.x = pk2c(h[0], h[1]); w.y = pk2c(h[2], h[3]);
;                     *(u32x2*)(H + (size_t)row * DM + 4 * lane + 256 * j) = w; }
	v_pk_mul_f32 v[136:137], v[82:83], v[82:83]
	v_pk_mul_f32 v[140:141], v[80:81], v[80:81]
	v_pk_add_f32 v[150:151], v[52:53], 1.0 op_sel_hi:[1,0]
	v_pk_mov_b32 v[146:147], v[140:141], v[136:137] op_sel:[1,0]
	v_mov_b32_e32 v141, v137
	v_pk_add_f32 v[136:137], v[146:147], v[140:141]
	v_pk_mul_f32 v[140:141], v[86:87], v[86:87]
	v_pk_add_f32 v[136:137], v[136:137], v[136:137] op_sel_hi:[0,1]
	v_pk_mul_f32 v[146:147], v[84:85], v[84:85]
	v_mul_f32_e32 v136, v88, v88
	v_pk_mov_b32 v[148:149], v[146:147], v[140:141] op_sel:[1,0]
	v_mov_b32_e32 v147, v141
	v_pk_add_f32 v[140:141], v[148:149], v[146:147]
	v_pk_fma_f32 v[146:147], v[88:89], v[88:89], v[136:137] op_sel_hi:[1,1,0]
	v_mul_f32_e32 v136, v90, v90
	v_pk_add_f32 v[140:141], v[140:141], v[140:141] op_sel_hi:[0,1]
	v_pk_fma_f32 v[148:149], v[90:91], v[90:91], v[136:137] op_sel_hi:[1,1,0]
	v_mul_f32_e32 v146, v92, v92
	v_mul_f32_e32 v148, v93, v93
	v_mul_f32_e32 v136, v94, v94
	v_mul_f32_e32 v140, v95, v95
	v_pk_add_f32 v[146:147], v[146:147], v[148:149]
	v_pk_add_f32 v[136:137], v[136:137], v[140:141]
	v_mov_b32_e32 v141, s19
	v_pk_add_f32 v[136:137], v[146:147], v[136:137]
	v_add_u32_e32 v140, 0xfffff000, v132
	v_add_f32_e32 v136, v136, v137
	ds_bpermute_b32 v103, v103, v136
	v_mov_b32_e32 v137, s1
	v_cndmask_b32_e64 v137, v137, v141, s[6:7]
	v_mov_b32_e32 v141, s18
	v_cndmask_b32_e64 v140, v132, v140, s[6:7]
	s_waitcnt lgkmcnt(0)
	v_add_f32_e32 v103, v136, v103
	ds_bpermute_b32 v105, v105, v103
	v_mov_b32_e32 v136, s0
	v_cndmask_b32_e64 v136, v136, v141, s[6:7]
	v_cndmask_b32_e64 v141, v133, 0, s[6:7]
	v_pk_add_f32 v[148:149], v[54:55], 1.0 op_sel_hi:[1,0]
	s_waitcnt lgkmcnt(0)
	v_add_f32_e32 v103, v103, v105
	ds_bpermute_b32 v105, v138, v103
	v_cndmask_b32_e64 v138, 23, 19, s[6:7]
	v_lshlrev_b64 v[146:147], v138, v[134:135]
	v_lshl_add_u64 v[136:137], v[136:137], 0, v[146:147]
	s_mov_b32 s6, 0x3a00000
	s_waitcnt lgkmcnt(0)
	v_add_f32_e32 v103, v103, v105
	ds_bpermute_b32 v105, v139, v103
	v_lshlrev_b64 v[138:139], 11, v[140:141]
	v_lshl_add_u64 v[136:137], v[136:137], 0, v[138:139]
	v_lshl_add_u64 v[136:137], v[136:137], 0, v[96:97]
	v_cvt_pk_bf16_f32 v138, v80, v81
	s_waitcnt lgkmcnt(0)
	v_add_f32_e32 v103, v103, v105
	v_xor_b32_e32 v105, 16, v227
	v_cmp_lt_i32_e32 vcc, v105, v99
	v_cvt_pk_bf16_f32 v139, v82, v83
	global_store_dwordx2 v[136:137], v[138:139], off
	v_cvt_pk_bf16_f32 v138, v84, v85
	v_cvt_pk_bf16_f32 v139, v86, v87
	global_store_dwordx2 v[136:137], v[138:139], off offset:512
	v_cndmask_b32_e32 v105, v227, v105, vcc
	v_lshlrev_b32_e32 v105, 2, v105
	ds_bpermute_b32 v105, v105, v103
	v_cvt_pk_bf16_f32 v138, v88, v89
	v_cvt_pk_bf16_f32 v139, v90, v91
	global_store_dwordx2 v[136:137], v[138:139], off offset:1024
	v_cvt_pk_bf16_f32 v138, v92, v93
	s_waitcnt lgkmcnt(0)
	v_add_f32_e32 v103, v103, v105
	v_xor_b32_e32 v105, 32, v227
	v_cmp_lt_i32_e32 vcc, v105, v99
	v_cvt_pk_bf16_f32 v139, v94, v95
	global_store_dwordx2 v[136:137], v[138:139], off offset:1536
	v_lshl_add_u64 v[138:139], s[8:9], 0, v[108:109]
	v_cndmask_b32_e32 v99, v227, v105, vcc
	v_lshlrev_b32_e32 v99, 2, v99
	ds_bpermute_b32 v99, v99, v103
	s_mov_b64 s[28:29], 0
	s_waitcnt lgkmcnt(0)
	v_add_f32_e32 v99, v103, v99
	v_fmamk_f32 v99, v99, 0x3a800000, v228
	v_mul_f32_e32 v103, 0x4b800000, v99
	v_cmp_gt_f32_e32 vcc, s39, v99
	s_nop 1
	v_cndmask_b32_e32 v99, v99, v103, vcc
	v_rsq_f32_e32 v99, v99
	s_nop 0
	v_mul_f32_e32 v103, 0x45800000, v99
	v_cndmask_b32_e32 v136, v99, v103, vcc
	v_pk_mul_f32 v[146:147], v[80:81], v[136:137] op_sel_hi:[1,0]
	v_pk_mul_f32 v[140:141], v[82:83], v[136:137] op_sel_hi:[1,0]
	v_pk_mul_f32 v[146:147], v[4:5], v[146:147]
	v_pk_mul_f32 v[140:141], v[6:7], v[140:141]
	v_pk_fma_f32 v[146:147], v[150:151], v[146:147], v[36:37]
	v_add_co_u32_e32 v138, vcc, s6, v138
	v_pk_fma_f32 v[140:141], v[148:149], v[140:141], v[38:39]
	v_cvt_pk_bf16_f32 v146, v146, v147
	s_nop 0
	v_addc_co_u32_e32 v139, vcc, 0, v139, vcc
	v_cvt_pk_bf16_f32 v147, v140, v141
	global_store_dwordx2 v[138:139], v[146:147], off
	v_pk_mul_f32 v[146:147], v[84:85], v[136:137] op_sel_hi:[1,0]
	v_pk_mul_f32 v[140:141], v[86:87], v[136:137] op_sel_hi:[1,0]
	v_pk_mul_f32 v[146:147], v[8:9], v[146:147]
	v_pk_add_f32 v[150:151], v[60:61], 1.0 op_sel_hi:[1,0]
	v_pk_mul_f32 v[140:141], v[10:11], v[140:141]
	v_pk_add_f32 v[148:149], v[62:63], 1.0 op_sel_hi:[1,0]
	v_pk_fma_f32 v[146:147], v[150:151], v[146:147], v[44:45]
	v_pk_fma_f32 v[140:141], v[148:149], v[140:141], v[46:47]
	v_cvt_pk_bf16_f32 v146, v146, v147
	v_pk_add_f32 v[148:149], v[58:59], 1.0 op_sel_hi:[1,0]
	v_cvt_pk_bf16_f32 v147, v140, v141
	global_store_dwordx2 v[138:139], v[146:147], off offset:512
	v_pk_mul_f32 v[140:141], v[90:91], v[136:137] op_sel_hi:[1,0]
	v_pk_mul_f32 v[146:147], v[88:89], v[136:137] op_sel_hi:[1,0]
	v_pk_mul_f32 v[140:141], v[26:27], v[140:141]
	v_pk_mul_f32 v[146:147], v[24:25], v[146:147]
	v_pk_add_f32 v[150:151], v[56:57], 1.0 op_sel_hi:[1,0]
	v_pk_fma_f32 v[140:141], v[148:149], v[140:141], v[42:43]
	v_pk_fma_f32 v[146:147], v[150:151], v[146:147], v[40:41]
	v_pk_add_f32 v[148:149], v[48:49], 1.0 op_sel_hi:[1,0]
	v_cvt_pk_bf16_f32 v146, v146, v147
	v_cvt_pk_bf16_f32 v147, v140, v141
	v_pk_mul_f32 v[140:141], v[94:95], v[136:137] op_sel_hi:[1,0]
	v_pk_mul_f32 v[136:137], v[92:93], v[136:137] op_sel_hi:[1,0]
	global_store_dwordx2 v[138:139], v[146:147], off offset:1024
	v_pk_mul_f32 v[136:137], v[20:21], v[136:137]
	v_pk_mul_f32 v[140:141], v[22:23], v[140:141]
	v_pk_add_f32 v[146:147], v[50:51], 1.0 op_sel_hi:[1,0]
	v_pk_fma_f32 v[136:137], v[148:149], v[136:137], v[32:33]
	v_pk_fma_f32 v[140:141], v[146:147], v[140:141], v[34:35]
	v_cvt_pk_bf16_f32 v136, v136, v137
	s_nop 0
	v_cvt_pk_bf16_f32 v137, v140, v141
	global_store_dwordx2 v[138:139], v[136:137], off offset:1536
	s_waitcnt vmcnt(8)
.LBB0_1285:
	s_andn2_b64 vcc, exec, s[28:29]
	s_cbranch_vccnz .LBB0_1272
	v_lshlrev_b64 v[134:135], 24, v[134:135]
	v_lshl_add_u64 v[134:135], s[0:1], 0, v[134:135]
	v_lshlrev_b64 v[132:133], 12, v[132:133]
	v_lshl_add_u64 v[132:133], v[134:135], 0, v[132:133]
	v_mov_b32_e32 v99, v97
	v_lshl_add_u64 v[132:133], v[132:133], 0, v[98:99]
	global_store_dwordx4 v[132:133], v[80:83], off
	global_store_dwordx4 v[132:133], v[84:87], off offset:1024
	global_store_dwordx4 v[132:133], v[88:91], off offset:2048
	global_store_dwordx4 v[132:133], v[92:95], off offset:3072
	s_waitcnt vmcnt(4)
	s_branch .LBB0_1272
